# Q|K planes re-laid out within each grid row ([q4][hf][g][t4][8]) so 4 consecutive lanes of an NA fragment load read 64 contiguous bytes
# speedup vs baseline: 1.0246x; 1.0047x over previous
; __device__ __forceinline__ u32x4v pack8(const f32x4& a, const f32x4& b) { u32x4v w; w.x = cvt_pk_bf16(a[0], a[1]); w.y = cvt_pk_bf16(a[2], a[3]); w.z = cvt_pk_bf16(b[0], b[1]); w.w = cvt_pk_bf16(b[2], b[3]); return w; }
;     __device__ __forceinline__ void operator()(const f32x4 (&acc)[2][2][4][2], const Unit& u, int wr, int wc, int fr, int fq) const {
;     ...
;             for (int m = 0; m < 4; ++m) { const int r = row0 + ai * HALF + m * 16; const float rs = rstd[r]; bf16_t* rowp = O + (size_t)r * ldc + col0;
; #pragma unroll
;                 for (int bj = 0; bj < 2; ++bj) { const f32x4 v0 = acc[ai][bj][m][0] * rs + bv[bj][0], v1 = acc[ai][bj][m][1] * rs + bv[bj][1];
;                     const int c = col0 + bj * HALF;
;                     (void)rowp; *(u32x4v*)(O + (((size_t)(c >> 6) * 2 + ((c >> 5) & 1)) * 32768 + r) * 32 + (c & 31)) = pack8(v0, v1); } }
; template <class Epi, class Sched, bool ALIGN_EPI = false, bool SP2 = false>
; __device__ __forceinline__ void gemm_phase(PG8_LAS unsigned char* lds, const Gemm g, const Sched& S, const Epi& E) {
;     ...
;     for (int i = 0; i < 2; ++i) { int R, C; stage_rc(tid * 16 + i * 8192, R, C); const int Rb = Epi::PERM ? ((R & ~31) + perm32(R & 31)) : R;
;         voffA[i] = (unsigned)(R * K + C) * 2u; voffB[i] = (unsigned)(Rb * K + C) * 2u; }
;     const size_t kstep = (size_t)(BK * 2);
;     const size_t hstep = (size_t)HALF * K * 2;
;     const size_t tstep = 2 * hstep;
;     const unsigned ldsw = (unsigned)wid * 1024u;
;     const int aoff = lds_byte(wr * 64 + fr, fq * 8), boff = lds_byte(wc * 32 + fr, fq * 8);
.LBB0_804:
	s_mov_b64 s[16:17], 0x80
	s_and_b32 s19, s1, 3
	s_add_i32 m0, s46, 0x18000
	v_lshl_add_u64 v[6:7], v[6:7], 0, s[16:17]
	s_lshl_b32 s26, s18, 13
	s_lshl_b32 s50, s19, 5
	s_waitcnt vmcnt(2)
	s_barrier
	global_load_lds_dwordx4 v[6:7], off
	v_lshl_add_u64 v[4:5], v[4:5], 0, s[16:17]
	s_add_i32 m0, s46, 0x1a000
	s_add_i32 s51, s46, 0x8000
	s_add_i32 s52, s46, 0xa000
	global_load_lds_dwordx4 v[4:5], off
	v_lshl_add_u64 v[0:1], v[0:1], 0, s[16:17]
	s_mov_b32 m0, s51
	s_add_u32 s20, s6, 0x40080
	global_load_lds_dwordx4 v[0:1], off
	v_lshl_add_u64 v[0:1], v[2:3], 0, s[16:17]
	s_mov_b32 m0, s52
	s_addc_u32 s21, s7, 0
	global_load_lds_dwordx4 v[0:1], off
	s_add_i32 m0, s46, 0x1c000
	v_lshl_add_u64 v[0:1], s[20:21], 0, v[148:149]
	global_load_lds_dwordx4 v[0:1], off
	v_lshl_add_u64 v[0:1], s[20:21], 0, v[152:153]
	s_add_i32 m0, s46, 0x1e000
	v_lshlrev_b32_e32 v2, 11, v170
	global_load_lds_dwordx4 v[0:1], off
	v_lshlrev_b32_e32 v1, 2, v145
	v_lshl_or_b32 v0, v145, 6, v172
	v_and_b32_e32 v1, 32, v1
	v_bitop3_b32 v0, v0, s26, v1 bitop3:0xde
	v_lshlrev_b32_e32 v1, 8, v221
	v_and_b32_e32 v1, 0x38000, v1
	v_or3_b32 v1, v168, v1, v2
	v_add_u32_e32 v156, v1, v169
	v_lshlrev_b32_e32 v1, 4, v171
	s_waitcnt vmcnt(6)
	s_cmpk_lt_u32 s12, 0x100
	v_and_b32_e32 v1, 0x78000, v1
	s_sext_i32_i8 s35, s0
	v_lshl_or_b32 v174, s18, 6, v145
	v_lshl_or_b32 v175, s19, 12, v173
	s_cselect_b64 s[18:19], -1, 0
	s_lshl_b32 s0, s1, 15
	v_or3_b32 v1, v168, v1, v2
	s_add_i32 s55, 0, 0x10000
	s_add_i32 s56, 0, 0x14000
	s_and_b32 s12, s0, 0x8000
	s_ashr_i32 s53, s74, 31
	s_mov_b32 s54, s74
	v_mov_b32_e32 v157, v155
	v_add_u32_e32 v158, v1, v169
	v_mov_b32_e32 v159, v155
	v_mov_b64_e32 v[160:161], 0x400
	v_mov_b64_e32 v[162:163], 0x3ff
	v_add_u32_e32 v176, s55, v175
	v_add_u32_e32 v177, s56, v175
	v_add_u32_e32 v178, 0, v0
	v_lshlrev_b32_e32 v154, 1, v144
	v_lshlrev_b32_e32 v154, 7, v144
	v_bfe_u32 v254, v145, 2, 1
	v_lshl_or_b32 v154, v254, 9, v154
	v_lshrrev_b32_e32 v254, 3, v145
	v_lshl_or_b32 v154, v254, 6, v154
	v_and_b32_e32 v254, 3, v145
	v_lshl_or_b32 v154, v254, 4, v154
	v_lshlrev_b32_e32 v254, 6, v145
	v_sub_u32_e32 v154, v154, v254
	v_ashrrev_i32_e32 v155, 31, v154
	s_mov_b32 s57, s13
	s_barrier
	s_branch .LBB0_807

; __device__ __forceinline__ u32x4v pack8(const f32x4& a, const f32x4& b) { u32x4v w; w.x = cvt_pk_bf16(a[0], a[1]); w.y = cvt_pk_bf16(a[2], a[3]); w.z = cvt_pk_bf16(b[0], b[1]); w.w = cvt_pk_bf16(b[2], b[3]); return w; }
;     __device__ __forceinline__ void operator()(const f32x4 (&acc)[2][2][4][2], const Unit& u, int wr, int wc, int fr, int fq) const {
;         const int row0 = u.pm * BM + wr * 64 + fr, col0 = u.pn * BM + wc * 32 + 8 * fq;
;         f32x4 bv[2][2];
; #pragma unroll
;         for (int bj = 0; bj < 2; ++bj)
; #pragma unroll
;             for (int n = 0; n < 2; ++n) bv[bj][n] = *(const f32x4*)(bias + col0 + bj * HALF + 4 * n);
; #pragma unroll
;         for (int ai = 0; ai < 2; ++ai)
; #pragma unroll
;             for (int m = 0; m < 4; ++m) { const int r = row0 + ai * HALF + m * 16; const float rs = rstd[r]; bf16_t* rowp = O + (size_t)r * ldc + col0;
; #pragma unroll
;                 for (int bj = 0; bj < 2; ++bj) { const f32x4 v0 = acc[ai][bj][m][0] * rs + bv[bj][0], v1 = acc[ai][bj][m][1] * rs + bv[bj][1];
;                     const int c = col0 + bj * HALF;
;                     (void)rowp; *(u32x4v*)(O + (((size_t)(c >> 6) * 2 + ((c >> 5) & 1)) * 32768 + r) * 32 + (c & 31)) = pack8(v0, v1); } }
;     }
.LBB0_817:
	s_lshl_b32 s6, s35, 8
	s_or_b32 s6, s6, s50
	v_or_b32_e32 v128, s6, v144
	v_lshl_add_u32 v164, s34, 8, v174
	v_ashrrev_i32_e32 v129, 31, v128
	v_ashrrev_i32_e32 v165, 31, v164
	v_lshl_add_u64 v[128:129], v[128:129], 2, s[22:23]
	v_lshl_add_u64 v[166:167], v[164:165], 2, s[8:9]
	global_load_dword v180, v[166:167], off
	global_load_dword v222, v[166:167], off offset:64
	global_load_dword v224, v[166:167], off offset:128
	global_load_dword v226, v[166:167], off offset:192
	global_load_dword v228, v[166:167], off offset:512
	global_load_dword v230, v[166:167], off offset:576
	global_load_dword v232, v[166:167], off offset:640
	global_load_dword v234, v[166:167], off offset:704
	global_load_dwordx4 v[140:143], v[128:129], off
	global_load_dwordx4 v[136:139], v[128:129], off offset:16
	global_load_dwordx4 v[132:135], v[128:129], off offset:512
	s_nop 0
	global_load_dwordx4 v[128:131], v[128:129], off offset:528
	s_ashr_i32 s10, s6, 6
	s_ashr_i32 s11, s10, 31
	s_lshl_b64 s[6:7], s[10:11], 22
	s_add_u32 s6, s40, s6
	s_addc_u32 s7, s41, s7
	s_or_b32 s10, s10, 2
	s_ashr_i32 s11, s10, 31
	s_lshl_b64 s[10:11], s[10:11], 22
	v_lshl_add_u64 v[184:185], v[164:165], 0, s[12:13]
	s_add_u32 s34, s40, s10
	v_lshlrev_b64 v[184:185], 6, v[184:185]
	s_addc_u32 s35, s41, s11
	v_or_b32_e32 v182, 16, v164
	v_lshl_add_u64 v[188:189], s[6:7], 0, v[184:185]
	v_lshl_add_u64 v[184:185], s[34:35], 0, v[184:185]
	v_ashrrev_i32_e32 v183, 31, v182
	v_lshl_add_u64 v[188:189], v[188:189], 0, v[154:155]
	v_lshl_add_u64 v[184:185], v[184:185], 0, v[154:155]
	v_lshl_add_u64 v[186:187], v[182:183], 2, s[8:9]
	s_andn2_b64 vcc, exec, s[0:1]
	s_mov_b64 s[0:1], -1
	s_waitcnt vmcnt(0)
	v_pk_fma_f32 v[126:127], v[126:127], v[180:181], v[142:143] op_sel_hi:[1,0,1]
	v_pk_fma_f32 v[124:125], v[124:125], v[180:181], v[140:141] op_sel_hi:[1,0,1]
	v_pk_fma_f32 v[122:123], v[122:123], v[180:181], v[138:139] op_sel_hi:[1,0,1]
	v_pk_fma_f32 v[120:121], v[120:121], v[180:181], v[136:137] op_sel_hi:[1,0,1]
	v_pk_fma_f32 v[118:119], v[118:119], v[180:181], v[134:135] op_sel_hi:[1,0,1]
	v_pk_fma_f32 v[116:117], v[116:117], v[180:181], v[132:133] op_sel_hi:[1,0,1]
	v_pk_fma_f32 v[190:191], v[114:115], v[180:181], v[130:131] op_sel_hi:[1,0,1]
	v_pk_fma_f32 v[180:181], v[112:113], v[180:181], v[128:129] op_sel_hi:[1,0,1]
	v_cvt_pk_bf16_f32 v112, v124, v125
	v_cvt_pk_bf16_f32 v113, v126, v127
	v_cvt_pk_bf16_f32 v114, v120, v121
	v_cvt_pk_bf16_f32 v115, v122, v123
	global_store_dwordx4 v[188:189], v[112:115], off
	s_nop 1
	v_cvt_pk_bf16_f32 v112, v116, v117
	v_cvt_pk_bf16_f32 v113, v118, v119
	v_cvt_pk_bf16_f32 v114, v180, v181
	v_cvt_pk_bf16_f32 v115, v190, v191
	global_store_dwordx4 v[184:185], v[112:115], off
	s_nop 1
	v_lshl_add_u64 v[116:117], v[182:183], 0, s[12:13]
	v_lshlrev_b64 v[116:117], 6, v[116:117]
	v_or_b32_e32 v114, 32, v164
	v_lshl_add_u64 v[120:121], s[6:7], 0, v[116:117]
	v_lshl_add_u64 v[116:117], s[34:35], 0, v[116:117]
	v_ashrrev_i32_e32 v115, 31, v114
	v_lshl_add_u64 v[120:121], v[120:121], 0, v[154:155]
	v_lshl_add_u64 v[116:117], v[116:117], 0, v[154:155]
	v_lshl_add_u64 v[118:119], v[114:115], 2, s[8:9]
	v_pk_fma_f32 v[110:111], v[110:111], v[222:223], v[142:143] op_sel_hi:[1,0,1]
	v_pk_fma_f32 v[108:109], v[108:109], v[222:223], v[140:141] op_sel_hi:[1,0,1]
	v_pk_fma_f32 v[106:107], v[106:107], v[222:223], v[138:139] op_sel_hi:[1,0,1]
	v_pk_fma_f32 v[104:105], v[104:105], v[222:223], v[136:137] op_sel_hi:[1,0,1]
	v_pk_fma_f32 v[102:103], v[102:103], v[222:223], v[134:135] op_sel_hi:[1,0,1]
	v_pk_fma_f32 v[100:101], v[100:101], v[222:223], v[132:133] op_sel_hi:[1,0,1]
	v_pk_fma_f32 v[122:123], v[98:99], v[222:223], v[130:131] op_sel_hi:[1,0,1]
	v_pk_fma_f32 v[112:113], v[96:97], v[222:223], v[128:129] op_sel_hi:[1,0,1]
	v_cvt_pk_bf16_f32 v96, v108, v109
	v_cvt_pk_bf16_f32 v97, v110, v111
	v_cvt_pk_bf16_f32 v98, v104, v105
	v_cvt_pk_bf16_f32 v99, v106, v107
	global_store_dwordx4 v[120:121], v[96:99], off offset:-896
	s_nop 1
	v_cvt_pk_bf16_f32 v96, v100, v101
	v_cvt_pk_bf16_f32 v97, v102, v103
	v_cvt_pk_bf16_f32 v98, v112, v113
	v_cvt_pk_bf16_f32 v99, v122, v123
	global_store_dwordx4 v[116:117], v[96:99], off offset:-896
	s_nop 1
	v_lshl_add_u64 v[100:101], v[114:115], 0, s[12:13]
	v_lshlrev_b64 v[100:101], 6, v[100:101]
	v_or_b32_e32 v98, 48, v164
	v_lshl_add_u64 v[104:105], s[6:7], 0, v[100:101]
	v_lshl_add_u64 v[100:101], s[34:35], 0, v[100:101]
	v_ashrrev_i32_e32 v99, 31, v98
	v_lshl_add_u64 v[104:105], v[104:105], 0, v[154:155]
	v_lshl_add_u64 v[100:101], v[100:101], 0, v[154:155]
	v_lshl_add_u64 v[102:103], v[98:99], 2, s[8:9]
	v_pk_fma_f32 v[94:95], v[94:95], v[224:225], v[142:143] op_sel_hi:[1,0,1]
	v_pk_fma_f32 v[92:93], v[92:93], v[224:225], v[140:141] op_sel_hi:[1,0,1]
	v_pk_fma_f32 v[90:91], v[90:91], v[224:225], v[138:139] op_sel_hi:[1,0,1]
	v_pk_fma_f32 v[88:89], v[88:89], v[224:225], v[136:137] op_sel_hi:[1,0,1]
	v_pk_fma_f32 v[86:87], v[86:87], v[224:225], v[134:135] op_sel_hi:[1,0,1]
	v_pk_fma_f32 v[84:85], v[84:85], v[224:225], v[132:133] op_sel_hi:[1,0,1]
	v_pk_fma_f32 v[106:107], v[82:83], v[224:225], v[130:131] op_sel_hi:[1,0,1]
	v_pk_fma_f32 v[96:97], v[80:81], v[224:225], v[128:129] op_sel_hi:[1,0,1]
	v_cvt_pk_bf16_f32 v80, v92, v93
	v_cvt_pk_bf16_f32 v81, v94, v95
	v_cvt_pk_bf16_f32 v82, v88, v89
	v_cvt_pk_bf16_f32 v83, v90, v91
	global_store_dwordx4 v[104:105], v[80:83], off offset:-1792
	s_nop 1
	v_cvt_pk_bf16_f32 v80, v84, v85
	v_cvt_pk_bf16_f32 v81, v86, v87
	v_cvt_pk_bf16_f32 v82, v96, v97
	v_cvt_pk_bf16_f32 v83, v106, v107
	global_store_dwordx4 v[100:101], v[80:83], off offset:-1792
	s_nop 1
	v_pk_fma_f32 v[78:79], v[78:79], v[226:227], v[142:143] op_sel_hi:[1,0,1]
; __device__ __forceinline__ u32x4v pack8(const f32x4& a, const f32x4& b) { u32x4v w; w.x = cvt_pk_bf16(a[0], a[1]); w.y = cvt_pk_bf16(a[2], a[3]); w.z = cvt_pk_bf16(b[0], b[1]); w.w = cvt_pk_bf16(b[2], b[3]); return w; }
;     __device__ __forceinline__ void operator()(const f32x4 (&acc)[2][2][4][2], const Unit& u, int wr, int wc, int fr, int fq) const {
;     ...
;             for (int m = 0; m < 4; ++m) { const int r = row0 + ai * HALF + m * 16; const float rs = rstd[r]; bf16_t* rowp = O + (size_t)r * ldc + col0;
; #pragma unroll
;                 for (int bj = 0; bj < 2; ++bj) { const f32x4 v0 = acc[ai][bj][m][0] * rs + bv[bj][0], v1 = acc[ai][bj][m][1] * rs + bv[bj][1];
;                     const int c = col0 + bj * HALF;
;                     (void)rowp; *(u32x4v*)(O + (((size_t)(c >> 6) * 2 + ((c >> 5) & 1)) * 32768 + r) * 32 + (c & 31)) = pack8(v0, v1); } }
;     }
	v_lshl_add_u64 v[82:83], v[98:99], 0, s[12:13]
	v_lshlrev_b64 v[82:83], 6, v[82:83]
	v_lshl_add_u64 v[84:85], s[6:7], 0, v[82:83]
	v_lshl_add_u64 v[82:83], s[34:35], 0, v[82:83]
	v_lshl_add_u64 v[84:85], v[84:85], 0, v[154:155]
	v_lshl_add_u64 v[82:83], v[82:83], 0, v[154:155]
	v_pk_fma_f32 v[76:77], v[76:77], v[226:227], v[140:141] op_sel_hi:[1,0,1]
	v_pk_fma_f32 v[74:75], v[74:75], v[226:227], v[138:139] op_sel_hi:[1,0,1]
	v_pk_fma_f32 v[72:73], v[72:73], v[226:227], v[136:137] op_sel_hi:[1,0,1]
	v_pk_fma_f32 v[70:71], v[70:71], v[226:227], v[134:135] op_sel_hi:[1,0,1]
	v_pk_fma_f32 v[68:69], v[68:69], v[226:227], v[132:133] op_sel_hi:[1,0,1]
	v_pk_fma_f32 v[86:87], v[66:67], v[226:227], v[130:131] op_sel_hi:[1,0,1]
	v_pk_fma_f32 v[80:81], v[64:65], v[226:227], v[128:129] op_sel_hi:[1,0,1]
	v_cvt_pk_bf16_f32 v64, v76, v77
	v_cvt_pk_bf16_f32 v65, v78, v79
	v_cvt_pk_bf16_f32 v66, v72, v73
	v_cvt_pk_bf16_f32 v67, v74, v75
	global_store_dwordx4 v[84:85], v[64:67], off offset:-2688
	s_nop 1
	v_cvt_pk_bf16_f32 v64, v68, v69
	v_cvt_pk_bf16_f32 v65, v70, v71
	v_cvt_pk_bf16_f32 v66, v80, v81
	v_cvt_pk_bf16_f32 v67, v86, v87
	global_store_dwordx4 v[82:83], v[64:67], off offset:-2688
	s_nop 1
	v_pk_fma_f32 v[62:63], v[62:63], v[228:229], v[142:143] op_sel_hi:[1,0,1]
	v_add_u32_e32 v66, 0x80, v164
	v_ashrrev_i32_e32 v67, 31, v66
	v_lshl_add_u64 v[66:67], v[66:67], 0, s[12:13]
	v_lshlrev_b64 v[66:67], 6, v[66:67]
	v_lshl_add_u64 v[68:69], s[6:7], 0, v[66:67]
	v_lshl_add_u64 v[66:67], s[34:35], 0, v[66:67]
	v_lshl_add_u64 v[68:69], v[68:69], 0, v[154:155]
	v_lshl_add_u64 v[66:67], v[66:67], 0, v[154:155]
	v_pk_fma_f32 v[60:61], v[60:61], v[228:229], v[140:141] op_sel_hi:[1,0,1]
	v_pk_fma_f32 v[58:59], v[58:59], v[228:229], v[138:139] op_sel_hi:[1,0,1]
	v_pk_fma_f32 v[56:57], v[56:57], v[228:229], v[136:137] op_sel_hi:[1,0,1]
	v_pk_fma_f32 v[54:55], v[54:55], v[228:229], v[134:135] op_sel_hi:[1,0,1]
	v_pk_fma_f32 v[52:53], v[52:53], v[228:229], v[132:133] op_sel_hi:[1,0,1]
	v_pk_fma_f32 v[70:71], v[50:51], v[228:229], v[130:131] op_sel_hi:[1,0,1]
	v_pk_fma_f32 v[64:65], v[48:49], v[228:229], v[128:129] op_sel_hi:[1,0,1]
	v_cvt_pk_bf16_f32 v48, v60, v61
	v_cvt_pk_bf16_f32 v49, v62, v63
	v_cvt_pk_bf16_f32 v50, v56, v57
	v_cvt_pk_bf16_f32 v51, v58, v59
	global_store_dwordx4 v[68:69], v[48:51], off
	s_nop 1
	v_cvt_pk_bf16_f32 v48, v52, v53
	v_cvt_pk_bf16_f32 v49, v54, v55
	v_cvt_pk_bf16_f32 v50, v64, v65
	v_cvt_pk_bf16_f32 v51, v70, v71
	global_store_dwordx4 v[66:67], v[48:51], off
	s_nop 1
	v_pk_fma_f32 v[46:47], v[46:47], v[230:231], v[142:143] op_sel_hi:[1,0,1]
	v_add_u32_e32 v50, 0x90, v164
	v_ashrrev_i32_e32 v51, 31, v50
	v_lshl_add_u64 v[50:51], v[50:51], 0, s[12:13]
	v_lshlrev_b64 v[50:51], 6, v[50:51]
	v_lshl_add_u64 v[52:53], s[6:7], 0, v[50:51]
	v_lshl_add_u64 v[50:51], s[34:35], 0, v[50:51]
	v_lshl_add_u64 v[52:53], v[52:53], 0, v[154:155]
	v_lshl_add_u64 v[50:51], v[50:51], 0, v[154:155]
	v_pk_fma_f32 v[44:45], v[44:45], v[230:231], v[140:141] op_sel_hi:[1,0,1]
	v_pk_fma_f32 v[42:43], v[42:43], v[230:231], v[138:139] op_sel_hi:[1,0,1]
	v_pk_fma_f32 v[40:41], v[40:41], v[230:231], v[136:137] op_sel_hi:[1,0,1]
	v_pk_fma_f32 v[38:39], v[38:39], v[230:231], v[134:135] op_sel_hi:[1,0,1]
	v_pk_fma_f32 v[36:37], v[36:37], v[230:231], v[132:133] op_sel_hi:[1,0,1]
	v_pk_fma_f32 v[54:55], v[34:35], v[230:231], v[130:131] op_sel_hi:[1,0,1]
	v_pk_fma_f32 v[48:49], v[32:33], v[230:231], v[128:129] op_sel_hi:[1,0,1]
	v_cvt_pk_bf16_f32 v32, v44, v45
	v_cvt_pk_bf16_f32 v33, v46, v47
	v_cvt_pk_bf16_f32 v34, v40, v41
	v_cvt_pk_bf16_f32 v35, v42, v43
	global_store_dwordx4 v[52:53], v[32:35], off offset:-896
	s_nop 1
	v_cvt_pk_bf16_f32 v32, v36, v37
	v_cvt_pk_bf16_f32 v33, v38, v39
	v_cvt_pk_bf16_f32 v34, v48, v49
	v_cvt_pk_bf16_f32 v35, v54, v55
	global_store_dwordx4 v[50:51], v[32:35], off offset:-896
	s_nop 1
	v_pk_fma_f32 v[30:31], v[30:31], v[232:233], v[142:143] op_sel_hi:[1,0,1]
	v_add_u32_e32 v34, 0xa0, v164
	v_ashrrev_i32_e32 v35, 31, v34
	v_lshl_add_u64 v[34:35], v[34:35], 0, s[12:13]
	v_lshlrev_b64 v[34:35], 6, v[34:35]
	v_lshl_add_u64 v[36:37], s[6:7], 0, v[34:35]
	v_lshl_add_u64 v[34:35], s[34:35], 0, v[34:35]
	v_lshl_add_u64 v[36:37], v[36:37], 0, v[154:155]
	v_lshl_add_u64 v[34:35], v[34:35], 0, v[154:155]
	v_pk_fma_f32 v[28:29], v[28:29], v[232:233], v[140:141] op_sel_hi:[1,0,1]
	v_pk_fma_f32 v[26:27], v[26:27], v[232:233], v[138:139] op_sel_hi:[1,0,1]
	v_pk_fma_f32 v[24:25], v[24:25], v[232:233], v[136:137] op_sel_hi:[1,0,1]
	v_pk_fma_f32 v[22:23], v[22:23], v[232:233], v[134:135] op_sel_hi:[1,0,1]
	v_pk_fma_f32 v[20:21], v[20:21], v[232:233], v[132:133] op_sel_hi:[1,0,1]
	v_pk_fma_f32 v[38:39], v[18:19], v[232:233], v[130:131] op_sel_hi:[1,0,1]
	v_pk_fma_f32 v[32:33], v[16:17], v[232:233], v[128:129] op_sel_hi:[1,0,1]
	v_cvt_pk_bf16_f32 v16, v28, v29
	v_cvt_pk_bf16_f32 v17, v30, v31
	v_cvt_pk_bf16_f32 v18, v24, v25
	v_cvt_pk_bf16_f32 v19, v26, v27
	global_store_dwordx4 v[36:37], v[16:19], off offset:-1792
	s_nop 1
	v_cvt_pk_bf16_f32 v16, v20, v21
	v_cvt_pk_bf16_f32 v17, v22, v23
	v_cvt_pk_bf16_f32 v18, v32, v33
	v_cvt_pk_bf16_f32 v19, v38, v39
	global_store_dwordx4 v[34:35], v[16:19], off offset:-1792
	s_nop 1
	v_pk_fma_f32 v[14:15], v[14:15], v[234:235], v[142:143] op_sel_hi:[1,0,1]
	v_add_u32_e32 v18, 0xb0, v164
	v_ashrrev_i32_e32 v19, 31, v18
	v_lshl_add_u64 v[18:19], v[18:19], 0, s[12:13]
	v_lshlrev_b64 v[18:19], 6, v[18:19]
	v_lshl_add_u64 v[20:21], s[6:7], 0, v[18:19]
	v_lshl_add_u64 v[18:19], s[34:35], 0, v[18:19]
	v_lshl_add_u64 v[20:21], v[20:21], 0, v[154:155]
	v_lshl_add_u64 v[18:19], v[18:19], 0, v[154:155]
	v_pk_fma_f32 v[12:13], v[12:13], v[234:235], v[140:141] op_sel_hi:[1,0,1]
	v_pk_fma_f32 v[10:11], v[10:11], v[234:235], v[138:139] op_sel_hi:[1,0,1]
	v_pk_fma_f32 v[8:9], v[8:9], v[234:235], v[136:137] op_sel_hi:[1,0,1]
	v_pk_fma_f32 v[6:7], v[6:7], v[234:235], v[134:135] op_sel_hi:[1,0,1]
	v_pk_fma_f32 v[4:5], v[4:5], v[234:235], v[132:133] op_sel_hi:[1,0,1]
	v_pk_fma_f32 v[22:23], v[2:3], v[234:235], v[130:131] op_sel_hi:[1,0,1]
	v_pk_fma_f32 v[16:17], v[0:1], v[234:235], v[128:129] op_sel_hi:[1,0,1]
	v_cvt_pk_bf16_f32 v0, v12, v13
	v_cvt_pk_bf16_f32 v1, v14, v15
	v_cvt_pk_bf16_f32 v2, v8, v9
	v_cvt_pk_bf16_f32 v3, v10, v11
	global_store_dwordx4 v[20:21], v[0:3], off offset:-2688
	s_nop 1
	v_cvt_pk_bf16_f32 v0, v4, v5
	v_cvt_pk_bf16_f32 v1, v6, v7
	v_cvt_pk_bf16_f32 v2, v16, v17
	v_cvt_pk_bf16_f32 v3, v22, v23
	global_store_dwordx4 v[18:19], v[0:3], off offset:-2688
	s_cbranch_vccnz .LBB0_806
	s_andn2_b64 vcc, exec, s[14:15]
	s_cbranch_vccnz .LBB0_805
	s_barrier
	s_branch .LBB0_805

; #define LAS __attribute__((address_space(3)))
; __device__ __forceinline__ void na_phase(const Frame& F, const bf16* QH, const bf16* VB, const float* rpb, bf16* U) {
;     const bf16* KH = QH + (size_t)16 * MTOK * 64;
;     LAS float* RP = (LAS float*)F.lds;
;     for (int i = F.tid; i < 16 * 465; i += 512) RP[i] = rpb[i];
;     __syncthreads();
;     const int lane = F.lane, n = lane & 15, q4 = lane >> 4;
;     const int vcu = (F.G % 8 == 0) ? (F.bid % 8) * (F.G / 8) + F.bid / 8 : F.bid;
;     for (int br = vcu; br < MB * 256; br += F.G) {
;         const int b = br >> 8, r = br & 255;
;         const int rs = min(max(r - 4, 0), 248);
; #pragma unroll 1
;         for (int it = 0; it < 8; ++it) {
;             const int hj = it * 8 + F.wave, h = hj >> 2, j = hj & 3;
;             const int c0 = (j == 0) ? 0 : (j == 1) ? 8 : (j == 2) ? 24 : 32;
;             const int qcol = 16 * j + n, cs = min(max(qcol - 8, 0), 48);
.LBB0_899:
	s_cmp_lt_i32 s72, 10
	s_cselect_b64 s[4:5], -1, 0
	s_and_b64 s[36:37], s[4:5], s[0:1]
	s_andn2_b64 vcc, exec, s[36:37]
	s_cbranch_vccnz .LBB0_913
	v_lshlrev_b32_e32 v4, 2, v221
	v_add_u32_e32 v3, 0, v4
	s_waitcnt lgkmcnt(0)
	v_add_u32_e32 v6, 0x1000, v4
	v_add_u32_e32 v7, 0x2000, v4
	v_add_u32_e32 v8, 0x3000, v4
	v_add_u32_e32 v9, 0x4000, v4
	v_add_u32_e32 v26, 0x5000, v4
	v_add_u32_e32 v27, 0x6000, v4
	v_add_u32_e32 v28, 0x7000, v4
	global_load_dword v10, v4, s[24:25]
	global_load_dword v11, v4, s[24:25] offset:2048
	global_load_dword v12, v6, s[24:25]
	global_load_dword v13, v6, s[24:25] offset:2048
	global_load_dword v14, v7, s[24:25]
	global_load_dword v15, v7, s[24:25] offset:2048
	global_load_dword v16, v8, s[24:25]
	global_load_dword v17, v8, s[24:25] offset:2048
	global_load_dword v18, v9, s[24:25]
	global_load_dword v19, v9, s[24:25] offset:2048
	global_load_dword v20, v26, s[24:25]
	global_load_dword v21, v26, s[24:25] offset:2048
	global_load_dword v22, v27, s[24:25]
	global_load_dword v23, v27, s[24:25] offset:2048
	v_cmp_gt_u32_e32 vcc, 0x110, v221
	s_nop 1
	s_and_saveexec_b64 s[0:1], vcc
	global_load_dword v24, v28, s[24:25]
	s_mov_b64 exec, s[0:1]
	s_waitcnt vmcnt(0)
	ds_write_b32 v3, v10
	ds_write_b32 v3, v11 offset:2048
	ds_write_b32 v3, v12 offset:4096
	ds_write_b32 v3, v13 offset:6144
	ds_write_b32 v3, v14 offset:8192
	ds_write_b32 v3, v15 offset:10240
	ds_write_b32 v3, v16 offset:12288
	ds_write_b32 v3, v17 offset:14336
	ds_write_b32 v3, v18 offset:16384
	ds_write_b32 v3, v19 offset:18432
	ds_write_b32 v3, v20 offset:20480
	ds_write_b32 v3, v21 offset:22528
	ds_write_b32 v3, v22 offset:24576
	ds_write_b32 v3, v23 offset:26624
	s_and_saveexec_b64 s[0:1], vcc
	ds_write_b32 v3, v24 offset:28672
	s_mov_b64 exec, s[0:1]
	s_ashr_i32 s1, s2, 31
	s_lshr_b32 s1, s1, 29
	s_add_i32 s1, s2, s1
	s_ashr_i32 s3, s1, 3
	s_and_b32 s1, s1, -8
	s_sub_i32 s1, s2, s1
	s_ashr_i32 s4, s74, 3
	s_mul_i32 s1, s4, s1
	s_and_b32 s0, s74, 7
	s_add_i32 s1, s1, s3
	s_cmp_eq_u32 s0, 0
	s_cselect_b32 s3, s1, s2
	s_mov_b32 s47, 0
	s_cmpk_lt_i32 s3, 0x200
	s_waitcnt lgkmcnt(0)
	s_barrier
	s_cbranch_scc0 .LBB0_912
	v_mbcnt_lo_u32_b32 v3, -1, 0
	v_readlane_b32 s0, v248, 14
	v_mbcnt_hi_u32_b32 v3, -1, v3
	s_bfe_u32 s6, s0, 0x20006
	v_and_b32_e32 v5, 64, v3
	s_lshl_b32 s8, s6, 4
	v_xor_b32_e32 v4, 16, v3
	v_add_u32_e32 v5, 64, v5
	s_cmp_eq_u32 s6, 2
	v_cmp_lt_i32_e32 vcc, v4, v5
	v_and_b32_e32 v0, 15, v221
	v_lshrrev_b32_e32 v72, 4, v220
	s_cselect_b32 s7, 24, 32
	v_cndmask_b32_e32 v4, v3, v4, vcc
	s_lshr_b32 s46, s0, 8
	v_or_b32_e32 v1, s8, v0
	v_lshlrev_b32_e32 v48, 3, v72
	v_lshlrev_b32_e32 v73, 2, v4
	v_xor_b32_e32 v4, 32, v3
	s_lshl_b64 s[0:1], s[46:47], 22
	v_sub_u32_e64 v1, v1, 8 clamp
	v_cmp_lt_i32_e32 vcc, v4, v5
	v_lshl_or_b32 v52, v0, 4, s0
	v_mov_b32_e32 v53, s1
	v_add_u32_e32 v75, s8, v0
	v_sub_u32_e32 v0, v48, v0
	s_mul_i32 s1, s46, 0x744
	v_min_u32_e32 v49, 48, v1
	v_mov_b32_e32 v51, 0
	v_lshlrev_b32_e32 v1, 1, v221
	v_and_b32_e32 v2, 3, v221
	v_cndmask_b32_e32 v3, v3, v4, vcc
	v_lshl_or_b32 v50, s46, 7, v48
	s_mov_b64 s[4:5], 0x8000040
	v_subrev_u32_e32 v76, s8, v0
	s_add_i32 s33, s1, 0
	v_add_u32_e32 v57, 16, v49
	v_lshlrev_b32_e32 v74, 2, v3
	v_lshl_add_u64 v[54:55], v[50:51], 0, s[4:5]
	s_addk_i32 s33, 0x364
	v_and_or_b32 v56, v1, 24, v2
	s_cmp_eq_u32 s6, 0
	s_cselect_b32 s98, 0, s7
	s_cmp_eq_u32 s6, 1
	s_cselect_b32 s98, 8, s98
	s_lshl_b32 s98, s98, 3
	v_and_b32_e32 v252, 15, v221
	v_lshrrev_b32_e32 v253, 2, v252
	v_and_b32_e32 v254, 3, v252
	v_lshlrev_b32_e32 v249, 10, v72
	v_lshl_or_b32 v250, v254, 4, v249
	v_lshl_or_b32 v249, v253, 6, v250
	v_add_u32_e32 v249, s98, v249
	v_and_b32_e32 v254, 1, v253
	v_lshl_or_b32 v250, v254, 9, v250
	v_lshrrev_b32_e32 v254, 3, v252
	v_lshl_add_u32 v254, s6, 1, v254
	v_lshl_or_b32 v250, v254, 6, v250
	v_mov_b32_e32 v58, s0
	v_mov_b32_e32 v59, v53
	v_add_u32_e32 v77, 1, v76
	v_add_u32_e32 v78, 2, v76
	v_add_u32_e32 v79, 3, v76
	v_add_u32_e32 v80, 4, v76
	v_add_u32_e32 v81, 5, v76
	v_add_u32_e32 v82, 6, v76
	v_add_u32_e32 v83, 7, v76
	s_movk_i32 s52, 0x7c
	s_brev_b32 s53, 8
	s_mov_b32 s54, 0x10200000
	s_mov_b32 s55, 0x10001000
	s_mov_b32 s56, 0x10201000
	s_mov_b32 s57, 0x10002000
	s_mov_b32 s58, 0x10202000
	s_mov_b32 s59, 0x10003000
	s_mov_b32 s60, 0x10203000
	s_mov_b32 s61, 0x10004000
	s_mov_b32 s62, 0x10204000
	s_mov_b32 s63, 0x10005000
	s_mov_b32 s64, 0x10205000
	s_mov_b32 s65, 0x10006000
	s_mov_b32 s66, 0x10206000
	s_mov_b32 s67, 0x10007000
	s_mov_b32 s76, 0x10207000
	s_mov_b32 s77, 0xff61b1e6
	v_mov_b32_e32 v84, 0xff61b1e6
	s_brev_b32 s78, 40
	s_mov_b32 s79, 0x14002000
	s_mov_b32 s80, 0x14004000
	s_mov_b32 s81, 0x14006000
	s_mov_b32 s82, 0x14008000
	s_mov_b32 s83, 0x1400a000
	s_mov_b32 s84, 0x1400c000
	s_mov_b32 s85, 0x1400e000
	s_mov_b64 s[48:49], 0x800000
	s_mov_b64 s[50:51], 0x100
	s_mov_b32 s86, s3
	s_branch .LBB0_905

; __device__ __forceinline__ void na_phase(const Frame& F, const bf16* QH, const bf16* VB, const float* rpb, bf16* U) {
;     ...
;             const int hj = it * 8 + F.wave, h = hj >> 2, j = hj & 3;
;             const int c0 = (j == 0) ? 0 : (j == 1) ? 8 : (j == 2) ? 24 : 32;
;             const int qcol = 16 * j + n, cs = min(max(qcol - 8, 0), 48);
;             const size_t tokq = (size_t)b * SEQL + r * 64 + qcol;
;             bf16x8 qf[2];
; #pragma unroll
;             for (int ks = 0; ks < 2; ++ks) qf[ks] = *(const bf16x8*)(QH + (((size_t)h * 2 + ks) * MTOK + tokq) * 32 + q4 * 8);
;             f32x4 acc[16];
; #pragma unroll
;             for (int blk = 0; blk < 16; ++blk) { const int i = blk >> 1, hf = blk & 1;
;                 const size_t tokk = (size_t)b * SEQL + (rs + i) * 64 + c0 + 8 * (n >> 2) + 4 * hf + (n & 3);
;                 const bf16* kp = KH + ((size_t)h * 2 * MTOK + tokk) * 32 + q4 * 8; const bf16x8 k0 = *(const bf16x8*)kp, k1 = *(const bf16x8*)(kp + (size_t)MTOK * 32);
;                 f32x4 a = (f32x4){0.f, 0.f, 0.f, 0.f};
;                 a = __builtin_amdgcn_mfma_f32_16x16x32_bf16(k0, qf[0], a, 0, 0, 0);
;                 a = __builtin_amdgcn_mfma_f32_16x16x32_bf16(k1, qf[1], a, 0, 0, 0);
;                 acc[blk] = a; }
.LBB0_905:
	s_and_b32 s8, s86, 0xff
	v_sub_u32_e64 v0, s8, 4 clamp
	v_lshl_add_u32 v1, s8, 6, v75
	v_lshl_add_u32 v251, s8, 12, v250
	v_readfirstlane_b32 s0, v0
	s_cmpk_lt_u32 s0, 0xf8
	s_cselect_b32 s1, 0, 0
	s_cselect_b32 s0, s0, 0xf8
	s_and_b32 s4, s3, 0xffffff00
	s_ashr_i32 s5, s4, 31
	s_or_b64 s[4:5], s[0:1], s[4:5]
	s_lshl_b64 s[4:5], s[4:5], 13
	v_lshl_add_u64 v[60:61], v[52:53], 0, s[4:5]
	s_ashr_i32 s4, s3, 8
	v_min_u32_e32 v0, 0xf8, v0
	s_ashr_i32 s5, s4, 31
	v_mul_lo_u32 v0, v0, s52
	s_mulk_i32 s8, 0x7c
	s_lshl_b64 s[10:11], s[4:5], 25
	v_lshlrev_b32_e32 v50, 11, v1
	v_subrev_u32_e32 v0, s8, v0
	s_lshl_b64 s[8:9], s[4:5], 14
	v_lshl_add_u64 v[2:3], v[54:55], 0, s[10:11]
	v_lshl_add_u64 v[62:63], v[2:3], 0, v[50:51]
	v_mov_b32_e32 v2, s8
	s_lshl_b32 s46, s0, 12
	v_lshl_or_b32 v64, s0, 6, v2
	s_lshl_b64 s[0:1], s[4:5], 20
	v_add_u32_e32 v85, s33, v0
	v_mov_b32_e32 v0, v251
	v_mov_b32_e32 v1, v51
	v_lshl_add_u64 v[2:3], v[58:59], 0, s[0:1]
	v_mov_b32_e32 v65, s9
	v_lshl_add_u64 v[66:67], v[2:3], 0, s[46:47]
	v_lshl_add_u64 v[68:69], v[2:3], 0, v[0:1]
	v_mov_b64_e32 v[70:71], v[58:59]
	v_add_u32_e32 v70, v249, v70
	v_add_u32_e32 v66, v249, v66
	s_mov_b32 s87, s47
	s_branch .LBB0_907
.LBB0_906:
	v_lshl_add_u64 v[0:1], s[70:71], 0, v[68:69]
	v_add_co_u32_e32 v2, vcc, 0xc000000, v0
	v_mov_b32_e32 v50, 0
	s_nop 0
	v_addc_co_u32_e32 v3, vcc, 0, v1, vcc
	v_add_co_u32_e32 v4, vcc, 0xc200000, v0
	v_lshl_add_u64 v[68:69], v[68:69], 0, s[48:49]
	s_nop 0
	v_addc_co_u32_e32 v5, vcc, 0, v1, vcc
	global_load_dwordx4 v[0:3], v[2:3], off
	s_nop 0
	global_load_dwordx4 v[86:89], v[4:5], off
	v_lshl_add_u64 v[4:5], v[64:65], 0, 0
	v_lshlrev_b64 v[4:5], 6, v[4:5]
	v_lshl_add_u64 v[4:5], v[70:71], 0, v[4:5]
	v_lshl_add_u64 v[4:5], s[70:71], 0, v[4:5]
	v_add_co_u32_e32 v8, vcc, 0x10000000, v4
	v_lshl_add_u64 v[70:71], v[70:71], 0, s[48:49]
	s_nop 0
	v_addc_co_u32_e32 v9, vcc, 0, v5, vcc
	v_add_co_u32_e32 v12, vcc, 0x10200000, v4
	s_nop 1
	v_addc_co_u32_e32 v13, vcc, 0, v5, vcc
	v_lshl_add_u64 v[4:5], v[66:67], 0, v[50:51]
	v_lshl_add_u64 v[114:115], s[70:71], 0, v[4:5]
	v_add_co_u32_e32 v106, vcc, s61, v114
	v_add_u32_e32 v50, s46, v48
	s_nop 0
	v_addc_co_u32_e32 v107, vcc, 0, v115, vcc
	v_add_co_u32_e32 v16, vcc, s53, v114
	global_load_dwordx4 v[4:7], v[106:107], off offset:-4096
	s_nop 0
	global_load_dwordx4 v[8:11], v[8:9], off
	s_nop 0
	global_load_dwordx4 v[12:15], v[12:13], off
	v_addc_co_u32_e32 v17, vcc, 0, v115, vcc
	v_add_co_u32_e32 v28, vcc, s54, v114
	s_mov_b64 s[0:1], vcc
	v_add_co_u32_e32 v20, vcc, s55, v114
	global_load_dwordx4 v[16:19], v[16:17], off offset:512
	s_nop 0
	v_addc_co_u32_e32 v21, vcc, 0, v115, vcc
	global_load_dwordx4 v[20:23], v[20:21], off offset:512
	s_nop 0
	global_load_dwordx4 v[24:27], v[106:107], off
	v_addc_co_u32_e64 v29, vcc, 0, v115, s[0:1]
	v_add_co_u32_e32 v36, vcc, s57, v114
	global_load_dwordx4 v[28:31], v[28:29], off offset:512
	s_nop 0
	v_addc_co_u32_e32 v37, vcc, 0, v115, vcc
	v_add_co_u32_e32 v38, vcc, s56, v114
	global_load_dwordx4 v[32:35], v[36:37], off offset:-4096
	s_nop 0
	v_addc_co_u32_e32 v39, vcc, 0, v115, vcc
	v_add_co_u32_e32 v40, vcc, s58, v114
	v_cmp_lt_u32_e64 s[0:1], v50, v57
	s_nop 0
	v_addc_co_u32_e32 v41, vcc, 0, v115, vcc
	v_add_co_u32_e32 v108, vcc, s62, v114
	v_lshl_add_u64 v[66:67], v[66:67], 0, s[48:49]
	s_nop 0
	v_addc_co_u32_e32 v109, vcc, 0, v115, vcc
	s_waitcnt vmcnt(7)
	v_mfma_f32_16x16x32_bf16 v[4:7], v[4:7], v[0:3], 0
	s_waitcnt vmcnt(6)
	v_mfma_f32_16x16x32_bf16 v[8:11], v[8:11], v[0:3], 0
	s_waitcnt vmcnt(5)
	v_mfma_f32_16x16x32_bf16 v[90:93], v[12:15], v[86:89], v[8:11]
	s_waitcnt vmcnt(3)
	v_mfma_f32_16x16x32_bf16 v[12:15], v[20:23], v[0:3], 0
	s_nop 3
	global_load_dwordx4 v[8:11], v[38:39], off offset:512
	global_load_dwordx4 v[20:23], v[36:37], off
	s_nop 0
	global_load_dwordx4 v[36:39], v[36:37], off offset:512
	v_mfma_f32_16x16x32_bf16 v[16:19], v[16:19], v[0:3], 0
	s_waitcnt vmcnt(4)
	v_mfma_f32_16x16x32_bf16 v[94:97], v[28:31], v[86:89], v[16:19]
	s_nop 5
	global_load_dwordx4 v[16:19], v[40:41], off offset:-4096
	s_waitcnt vmcnt(4)
	v_mfma_f32_16x16x32_bf16 v[32:35], v[32:35], v[0:3], 0
	s_waitcnt vmcnt(3)
	v_mfma_f32_16x16x32_bf16 v[98:101], v[8:11], v[86:89], v[12:15]
	s_nop 2
	v_add_co_u32_e32 v12, vcc, s59, v114
	s_waitcnt vmcnt(1)
	v_mfma_f32_16x16x32_bf16 v[28:31], v[36:39], v[0:3], 0
	global_load_dwordx4 v[36:39], v[40:41], off
	s_nop 0
	global_load_dwordx4 v[40:43], v[40:41], off offset:512
	v_addc_co_u32_e32 v13, vcc, 0, v115, vcc
	global_load_dwordx4 v[8:11], v[108:109], off offset:-4096
	v_mfma_f32_16x16x32_bf16 v[20:23], v[20:23], v[0:3], 0
	global_load_dwordx4 v[12:15], v[12:13], off offset:512
	s_waitcnt vmcnt(4)
	v_mfma_f32_16x16x32_bf16 v[102:105], v[16:19], v[86:89], v[32:35]
	global_load_dwordx4 v[16:19], v[106:107], off offset:512
	s_waitcnt vmcnt(4)
	v_mfma_f32_16x16x32_bf16 v[44:47], v[36:39], v[86:89], v[20:23]
	s_nop 2
	v_add_co_u32_e32 v20, vcc, s60, v114
	s_nop 1
	v_addc_co_u32_e32 v21, vcc, 0, v115, vcc
	s_waitcnt vmcnt(2)
	v_mfma_f32_16x16x32_bf16 v[36:39], v[8:11], v[86:89], v[4:7]
	s_nop 2
	global_load_dwordx4 v[4:7], v[20:21], off offset:512
	s_waitcnt vmcnt(2)
	v_mfma_f32_16x16x32_bf16 v[8:11], v[12:15], v[0:3], 0
	v_mfma_f32_16x16x32_bf16 v[40:43], v[40:43], v[86:89], v[28:31]
	s_nop 2
	v_add_co_u32_e32 v28, vcc, s65, v114
	s_waitcnt vmcnt(0)
	v_mfma_f32_16x16x32_bf16 v[32:35], v[4:7], v[86:89], v[8:11]
	s_nop 2
	global_load_dwordx4 v[8:11], v[108:109], off
	global_load_dwordx4 v[12:15], v[108:109], off offset:512
	v_addc_co_u32_e32 v29, vcc, 0, v115, vcc
	v_mfma_f32_16x16x32_bf16 v[4:7], v[24:27], v[0:3], 0
	v_add_co_u32_e32 v110, vcc, s66, v114
	global_load_dwordx4 v[106:109], v[28:29], off offset:512
	s_waitcnt vmcnt(2)
; #define LAS __attribute__((address_space(3)))
; __device__ __forceinline__ void na_phase(const Frame& F, const bf16* QH, const bf16* VB, const float* rpb, bf16* U) {
;     ...
;             for (int blk = 0; blk < 16; ++blk) { const int i = blk >> 1, hf = blk & 1;
;                 const size_t tokk = (size_t)b * SEQL + (rs + i) * 64 + c0 + 8 * (n >> 2) + 4 * hf + (n & 3);
;                 const bf16* kp = KH + ((size_t)h * 2 * MTOK + tokk) * 32 + q4 * 8; const bf16x8 k0 = *(const bf16x8*)kp, k1 = *(const bf16x8*)(kp + (size_t)MTOK * 32);
;                 f32x4 a = (f32x4){0.f, 0.f, 0.f, 0.f};
;                 a = __builtin_amdgcn_mfma_f32_16x16x32_bf16(k0, qf[0], a, 0, 0, 0);
;                 a = __builtin_amdgcn_mfma_f32_16x16x32_bf16(k1, qf[1], a, 0, 0, 0);
;                 acc[blk] = a; }
;             float mx = -3.0e38f;
;             int cofs[8]; bool okk[8];
; #pragma unroll
;             for (int k8 = 0; k8 < 8; ++k8) { const int kc = c0 + 8 * q4 + 4 * (k8 >> 2) + (k8 & 3); okk[k8] = (kc >= cs) && (kc < cs + 16); cofs[k8] = min(max(kc - qcol + 15, 0), 30); }
; #pragma unroll
;             for (int i = 0; i < 8; ++i) { const LAS float* rprow = RP + (h * 15 + (rs + i - r + 7)) * 31;
; #pragma unroll
;                 for (int k8 = 0; k8 < 8; ++k8) { const int blk = 2 * i + (k8 >> 2), e = k8 & 3;
;                     const float bia = rprow[cofs[k8]];
;                     const float sb = acc[blk][e] * 0.125f + bia; const float s = okk[k8] ? sb : -3.0e38f;
;                     acc[blk][e] = s; mx = fmaxf(mx, s); } }
	v_mfma_f32_16x16x32_bf16 v[20:23], v[8:11], v[86:89], v[4:7]
	s_nop 3
	global_load_dwordx4 v[4:7], v[28:29], off offset:-4096
	v_addc_co_u32_e32 v111, vcc, 0, v115, vcc
	v_mfma_f32_16x16x32_bf16 v[8:11], v[16:19], v[0:3], 0
	global_load_dwordx4 v[16:19], v[110:111], off offset:-4096
	s_waitcnt vmcnt(3)
	v_mfma_f32_16x16x32_bf16 v[24:27], v[12:15], v[86:89], v[8:11]
	v_add_co_u32_e32 v12, vcc, s63, v114
	s_nop 1
	v_addc_co_u32_e32 v13, vcc, 0, v115, vcc
	global_load_dwordx4 v[12:15], v[12:13], off offset:512
	v_add_co_u32_e32 v112, vcc, s64, v114
	global_load_dwordx4 v[8:11], v[28:29], off
	s_nop 0
	v_addc_co_u32_e32 v113, vcc, 0, v115, vcc
	v_add_co_u32_e32 v116, vcc, s67, v114
	s_waitcnt vmcnt(3)
	v_mfma_f32_16x16x32_bf16 v[4:7], v[4:7], v[0:3], 0
	v_addc_co_u32_e32 v117, vcc, 0, v115, vcc
	v_add_co_u32_e32 v114, vcc, s76, v114
	s_waitcnt vmcnt(2)
	v_mfma_f32_16x16x32_bf16 v[28:31], v[16:19], v[86:89], v[4:7]
	v_addc_co_u32_e32 v115, vcc, 0, v115, vcc
	v_cmp_ge_u32_e32 vcc, v50, v49
	s_nop 1
	global_load_dwordx4 v[4:7], v[112:113], off offset:512
	s_waitcnt vmcnt(2)
	v_mfma_f32_16x16x32_bf16 v[12:15], v[12:15], v[0:3], 0
	s_and_b64 vcc, vcc, s[0:1]
	s_waitcnt vmcnt(0)
	v_mfma_f32_16x16x32_bf16 v[16:19], v[4:7], v[86:89], v[12:15]
	v_mfma_f32_16x16x32_bf16 v[4:7], v[8:11], v[0:3], 0
	global_load_dwordx4 v[8:11], v[110:111], off
	s_nop 0
	global_load_dwordx4 v[110:113], v[110:111], off offset:512
	s_waitcnt vmcnt(1)
	v_mfma_f32_16x16x32_bf16 v[12:15], v[8:11], v[86:89], v[4:7]
	s_nop 2
	global_load_dwordx4 v[4:7], v[116:117], off
	v_mfma_f32_16x16x32_bf16 v[8:11], v[106:109], v[0:3], 0
	global_load_dwordx4 v[106:109], v[114:115], off
	s_waitcnt vmcnt(2)
	v_mfma_f32_16x16x32_bf16 v[8:11], v[110:113], v[86:89], v[8:11]
	global_load_dwordx4 v[110:113], v[116:117], off offset:512
	s_nop 0
	global_load_dwordx4 v[114:117], v[114:115], off offset:512
	s_waitcnt vmcnt(3)
	v_mfma_f32_16x16x32_bf16 v[4:7], v[4:7], v[0:3], 0
	s_waitcnt vmcnt(1)
	v_mfma_f32_16x16x32_bf16 v[0:3], v[110:113], v[0:3], 0
	v_add_u32_e32 v110, s87, v85
	s_addk_i32 s87, 0xe88
	v_mfma_f32_16x16x32_bf16 v[4:7], v[106:109], v[86:89], v[4:7]
	s_waitcnt vmcnt(0)
	v_mfma_f32_16x16x32_bf16 v[0:3], v[114:117], v[86:89], v[0:3]
	v_or_b32_e32 v86, 1, v50
	v_cmp_ge_u32_e64 s[4:5], v86, v49
	v_cmp_lt_u32_e64 s[8:9], v86, v57
	v_or_b32_e32 v86, 2, v50
	v_cmp_ge_u32_e64 s[10:11], v86, v49
	v_cmp_lt_u32_e64 s[12:13], v86, v57
	v_or_b32_e32 v86, 3, v50
	v_cmp_ge_u32_e64 s[14:15], v86, v49
	v_cmp_lt_u32_e64 s[16:17], v86, v57
	v_or_b32_e32 v86, 4, v50
	v_cmp_ge_u32_e64 s[18:19], v86, v49
	v_cmp_lt_u32_e64 s[20:21], v86, v57
	v_or_b32_e32 v86, 5, v50
	v_cmp_ge_u32_e64 s[22:23], v86, v49
	v_cmp_lt_u32_e64 s[24:25], v86, v57
	v_or_b32_e32 v86, 6, v50
	v_cmp_ge_u32_e64 s[26:27], v86, v49
	v_cmp_lt_u32_e64 s[28:29], v86, v57
	v_add_u32_e32 v86, s46, v76
	v_add_u32_e32 v88, s46, v77
	v_max_i32_e32 v86, -15, v86
	v_max_i32_e32 v88, -15, v88
	v_add_u32_e32 v86, 15, v86
	v_add_u32_e32 v88, 15, v88
	v_min_u32_e32 v86, 30, v86
	v_min_u32_e32 v88, 30, v88
	v_lshl_add_u32 v112, v86, 2, v110
	v_lshl_add_u32 v113, v88, 2, v110
	ds_read2_b32 v[86:87], v112 offset1:31
	ds_read2_b32 v[88:89], v113 offset1:31
	v_or_b32_e32 v50, 7, v50
	v_cmp_ge_u32_e64 s[30:31], v50, v49
	v_cmp_lt_u32_e64 s[34:35], v50, v57
	s_waitcnt lgkmcnt(1)
	v_fmamk_f32 v50, v90, 0x3e000000, v86
	s_waitcnt lgkmcnt(0)
	v_fmamk_f32 v86, v91, 0x3e000000, v88
	s_and_b64 s[0:1], s[4:5], s[8:9]
	v_cndmask_b32_e64 v114, v84, v86, s[0:1]
	v_add_u32_e32 v86, s46, v78
	v_max_i32_e32 v86, -15, v86
	v_add_u32_e32 v86, 15, v86
	v_min_u32_e32 v86, 30, v86
	v_lshl_add_u32 v115, v86, 2, v110
	v_add_u32_e32 v86, s46, v79
	v_max_i32_e32 v86, -15, v86
	v_add_u32_e32 v86, 15, v86
	v_min_u32_e32 v86, 30, v86
	ds_read2_b32 v[90:91], v115 offset1:31
	v_lshl_add_u32 v116, v86, 2, v110
	ds_read2_b32 v[106:107], v116 offset1:31
	s_and_b64 s[4:5], s[10:11], s[12:13]
	s_and_b64 s[8:9], s[14:15], s[16:17]
	s_waitcnt lgkmcnt(1)
	v_fmamk_f32 v88, v92, 0x3e000000, v90
	v_cndmask_b32_e64 v117, v84, v88, s[4:5]
	s_waitcnt lgkmcnt(0)
	v_fmamk_f32 v88, v93, 0x3e000000, v106
	v_cndmask_b32_e64 v106, v84, v88, s[8:9]
	v_add_u32_e32 v88, s46, v80
	v_max_i32_e32 v88, -15, v88
	v_add_u32_e32 v88, 15, v88
	v_min_u32_e32 v88, 30, v88
	v_lshl_add_u32 v118, v88, 2, v110
	v_add_u32_e32 v88, s46, v81
	v_max_i32_e32 v88, -15, v88
	v_add_u32_e32 v88, 15, v88
	v_min_u32_e32 v88, 30, v88
	ds_read2_b32 v[92:93], v118 offset1:31
	v_lshl_add_u32 v119, v88, 2, v110
	ds_read2_b32 v[108:109], v119 offset1:31
	s_and_b64 s[10:11], s[18:19], s[20:21]
	s_and_b64 s[12:13], s[22:23], s[24:25]
	s_waitcnt lgkmcnt(1)
	v_fmamk_f32 v88, v94, 0x3e000000, v92
	v_cndmask_b32_e64 v120, v84, v88, s[10:11]
	s_waitcnt lgkmcnt(0)
	v_fmamk_f32 v88, v95, 0x3e000000, v108
	v_cndmask_b32_e64 v108, v84, v88, s[12:13]
	v_add_u32_e32 v88, s46, v82
	v_max_i32_e32 v88, -15, v88
	v_add_u32_e32 v88, 15, v88
	v_min_u32_e32 v88, 30, v88
	v_lshl_add_u32 v121, v88, 2, v110
	v_add_u32_e32 v88, s46, v83
	v_max_i32_e32 v88, -15, v88
	v_add_u32_e32 v88, 15, v88
	v_min_u32_e32 v88, 30, v88
	ds_read2_b32 v[94:95], v121 offset1:31
	v_lshl_add_u32 v122, v88, 2, v110
	ds_read2_b32 v[110:111], v122 offset1:31
	v_cndmask_b32_e32 v50, v84, v50, vcc
	v_max3_f32 v86, v50, s77, v114
	s_waitcnt lgkmcnt(1)
	v_fmamk_f32 v88, v96, 0x3e000000, v94
	s_and_b64 s[14:15], s[26:27], s[28:29]
	v_max3_f32 v86, v86, v117, v106
	v_cndmask_b32_e64 v96, v84, v88, s[14:15]
	s_waitcnt lgkmcnt(0)
; #define LAS __attribute__((address_space(3)))
; __device__ __forceinline__ void na_phase(const Frame& F, const bf16* QH, const bf16* VB, const float* rpb, bf16* U) {
;     ...
;             for (int k8 = 0; k8 < 8; ++k8) { const int kc = c0 + 8 * q4 + 4 * (k8 >> 2) + (k8 & 3); okk[k8] = (kc >= cs) && (kc < cs + 16); cofs[k8] = min(max(kc - qcol + 15, 0), 30); }
; #pragma unroll
;             for (int i = 0; i < 8; ++i) { const LAS float* rprow = RP + (h * 15 + (rs + i - r + 7)) * 31;
; #pragma unroll
;                 for (int k8 = 0; k8 < 8; ++k8) { const int blk = 2 * i + (k8 >> 2), e = k8 & 3;
;                     const float bia = rprow[cofs[k8]];
;                     const float sb = acc[blk][e] * 0.125f + bia; const float s = okk[k8] ? sb : -3.0e38f;
;                     acc[blk][e] = s; mx = fmaxf(mx, s); } }
	v_fmamk_f32 v88, v97, 0x3e000000, v110
	s_and_b64 s[16:17], s[30:31], s[34:35]
	v_max3_f32 v86, v86, v120, v108
	v_cndmask_b32_e64 v97, v84, v88, s[16:17]
	v_fmac_f32_e32 v87, 0x3e000000, v102
	v_fmac_f32_e32 v89, 0x3e000000, v103
	v_max3_f32 v86, v86, v96, v97
	v_cndmask_b32_e32 v102, v84, v87, vcc
	v_cndmask_b32_e64 v103, v84, v89, s[0:1]
	v_fmac_f32_e32 v91, 0x3e000000, v104
	v_fmac_f32_e32 v107, 0x3e000000, v105
	v_max3_f32 v86, v86, v102, v103
	v_cndmask_b32_e64 v104, v84, v91, s[4:5]
	v_cndmask_b32_e64 v105, v84, v107, s[8:9]
	v_fmac_f32_e32 v93, 0x3e000000, v98
	v_fmac_f32_e32 v109, 0x3e000000, v99
	v_max3_f32 v86, v86, v104, v105
	v_cndmask_b32_e64 v98, v84, v93, s[10:11]
	v_cndmask_b32_e64 v99, v84, v109, s[12:13]
	v_max3_f32 v90, v86, v98, v99
	ds_read2_b32 v[86:87], v112 offset0:62 offset1:93
	ds_read2_b32 v[88:89], v113 offset0:62 offset1:93
	v_fmac_f32_e32 v95, 0x3e000000, v100
	v_fmac_f32_e32 v111, 0x3e000000, v101
	v_cndmask_b32_e64 v100, v84, v95, s[14:15]
	v_cndmask_b32_e64 v101, v84, v111, s[16:17]
	s_waitcnt lgkmcnt(1)
	v_fmamk_f32 v44, v44, 0x3e000000, v86
	v_max3_f32 v92, v90, v100, v101
	v_cndmask_b32_e32 v86, v84, v44, vcc
	ds_read2_b32 v[90:91], v115 offset0:62 offset1:93
	s_waitcnt lgkmcnt(1)
	v_fmamk_f32 v44, v45, 0x3e000000, v88
	v_cndmask_b32_e64 v88, v84, v44, s[0:1]
	ds_read2_b32 v[44:45], v116 offset0:62 offset1:93
	v_max3_f32 v94, v92, v86, v88
	s_waitcnt lgkmcnt(1)
	v_fmamk_f32 v46, v46, 0x3e000000, v90
	ds_read2_b32 v[92:93], v118 offset0:62 offset1:93
	v_cndmask_b32_e64 v90, v84, v46, s[4:5]
	s_waitcnt lgkmcnt(1)
	v_fmamk_f32 v44, v47, 0x3e000000, v44
	ds_read2_b32 v[46:47], v119 offset0:62 offset1:93
	v_cndmask_b32_e64 v44, v84, v44, s[8:9]
	s_waitcnt lgkmcnt(1)
	v_fmamk_f32 v40, v40, 0x3e000000, v92
	v_max3_f32 v107, v94, v90, v44
	v_cndmask_b32_e64 v92, v84, v40, s[10:11]
	ds_read2_b32 v[94:95], v121 offset0:62 offset1:93
	s_waitcnt lgkmcnt(1)
	v_fmamk_f32 v46, v41, 0x3e000000, v46
	ds_read2_b32 v[40:41], v122 offset0:62 offset1:93
	v_cndmask_b32_e64 v46, v84, v46, s[12:13]
	v_fmac_f32_e32 v93, 0x3e000000, v32
	s_waitcnt lgkmcnt(1)
	v_fmamk_f32 v42, v42, 0x3e000000, v94
	v_fmac_f32_e32 v47, 0x3e000000, v33
	s_waitcnt lgkmcnt(0)
	v_fmamk_f32 v40, v43, 0x3e000000, v40
	ds_read2_b32 v[32:33], v112 offset0:124 offset1:155
	v_max3_f32 v107, v107, v92, v46
	v_cndmask_b32_e64 v42, v84, v42, s[14:15]
	v_cndmask_b32_e64 v43, v84, v40, s[16:17]
	v_fmac_f32_e32 v87, 0x3e000000, v36
	v_fmac_f32_e32 v89, 0x3e000000, v37
	v_fmac_f32_e32 v95, 0x3e000000, v34
	v_fmac_f32_e32 v41, 0x3e000000, v35
	ds_read2_b32 v[34:35], v113 offset0:124 offset1:155
	v_max3_f32 v40, v107, v42, v43
	v_cndmask_b32_e32 v87, v84, v87, vcc
	v_cndmask_b32_e64 v89, v84, v89, s[0:1]
	v_fmac_f32_e32 v91, 0x3e000000, v38
	v_fmac_f32_e32 v45, 0x3e000000, v39
	v_max3_f32 v36, v40, v87, v89
	v_cndmask_b32_e64 v91, v84, v91, s[4:5]
	v_cndmask_b32_e64 v45, v84, v45, s[8:9]
	v_max3_f32 v36, v36, v91, v45
	v_cndmask_b32_e64 v93, v84, v93, s[10:11]
	v_cndmask_b32_e64 v47, v84, v47, s[12:13]
	v_max3_f32 v36, v36, v93, v47
	v_cndmask_b32_e64 v94, v84, v95, s[14:15]
	v_cndmask_b32_e64 v95, v84, v41, s[16:17]
	s_waitcnt lgkmcnt(1)
	v_fmamk_f32 v20, v20, 0x3e000000, v32
	v_max3_f32 v38, v36, v94, v95
	v_cndmask_b32_e32 v107, v84, v20, vcc
	ds_read2_b32 v[36:37], v115 offset0:124 offset1:155
	s_waitcnt lgkmcnt(1)
	v_fmamk_f32 v20, v21, 0x3e000000, v34
	v_cndmask_b32_e64 v34, v84, v20, s[0:1]
	ds_read2_b32 v[20:21], v116 offset0:124 offset1:155
	v_max3_f32 v32, v38, v107, v34
	s_waitcnt lgkmcnt(1)
	v_fmamk_f32 v22, v22, 0x3e000000, v36
	ds_read2_b32 v[38:39], v118 offset0:124 offset1:155
	v_cndmask_b32_e64 v36, v84, v22, s[4:5]
	s_waitcnt lgkmcnt(1)
	v_fmamk_f32 v20, v23, 0x3e000000, v20
	ds_read2_b32 v[22:23], v119 offset0:124 offset1:155
	ds_read2_b32 v[40:41], v121 offset0:124 offset1:155
	s_waitcnt lgkmcnt(2)
	v_fmamk_f32 v24, v24, 0x3e000000, v38
	v_cndmask_b32_e64 v38, v84, v24, s[10:11]
	v_cndmask_b32_e64 v109, v84, v20, s[8:9]
	s_waitcnt lgkmcnt(1)
	v_fmamk_f32 v22, v25, 0x3e000000, v22
	ds_read2_b32 v[24:25], v122 offset0:124 offset1:155
	v_cndmask_b32_e64 v110, v84, v22, s[12:13]
	s_waitcnt lgkmcnt(1)
	v_fmamk_f32 v22, v26, 0x3e000000, v40
	v_max3_f32 v20, v32, v36, v109
	v_cndmask_b32_e64 v40, v84, v22, s[14:15]
	s_waitcnt lgkmcnt(0)
	v_fmamk_f32 v22, v27, 0x3e000000, v24
	v_max3_f32 v20, v20, v38, v110
	v_cndmask_b32_e64 v111, v84, v22, s[16:17]
	v_fmac_f32_e32 v33, 0x3e000000, v28
	v_fmac_f32_e32 v35, 0x3e000000, v29
	v_max3_f32 v20, v20, v40, v111
	v_cndmask_b32_e32 v123, v84, v33, vcc
	v_cndmask_b32_e64 v35, v84, v35, s[0:1]
	v_fmac_f32_e32 v37, 0x3e000000, v30
	v_fmac_f32_e32 v21, 0x3e000000, v31
	v_max3_f32 v20, v20, v123, v35
	v_cndmask_b32_e64 v37, v84, v37, s[4:5]
	v_cndmask_b32_e64 v124, v84, v21, s[8:9]
	v_fmac_f32_e32 v39, 0x3e000000, v16
	v_fmac_f32_e32 v23, 0x3e000000, v17
	v_max3_f32 v20, v20, v37, v124
	v_cndmask_b32_e64 v125, v84, v39, s[10:11]
	v_cndmask_b32_e64 v126, v84, v23, s[12:13]
	v_max3_f32 v16, v20, v125, v126
	ds_read2_b32 v[20:21], v112 offset0:186 offset1:217
	v_fmac_f32_e32 v41, 0x3e000000, v18
	v_fmac_f32_e32 v25, 0x3e000000, v19
	ds_read2_b32 v[18:19], v113 offset0:186 offset1:217
	v_cndmask_b32_e64 v127, v84, v41, s[14:15]
	v_cndmask_b32_e64 v112, v84, v25, s[16:17]
	s_waitcnt lgkmcnt(1)
	v_fmamk_f32 v12, v12, 0x3e000000, v20
	v_max3_f32 v26, v16, v127, v112
	v_cndmask_b32_e32 v16, v84, v12, vcc
	s_waitcnt lgkmcnt(0)
; __device__ __forceinline__ void na_phase(const Frame& F, const bf16* QH, const bf16* VB, const float* rpb, bf16* U) {
;     ...
;                     acc[blk][e] = s; mx = fmaxf(mx, s); } }
;             mx = fmaxf(mx, __shfl_xor(mx, 16)); mx = fmaxf(mx, __shfl_xor(mx, 32));
;             float sum = 0.f;
; #pragma unroll
;             for (int blk = 0; blk < 16; ++blk)
; #pragma unroll
;                 for (int e = 0; e < 4; ++e) { const float p = __builtin_amdgcn_exp2f((acc[blk][e] - mx) * 1.44269504089f); acc[blk][e] = p; sum += p; }
	v_fmamk_f32 v12, v13, 0x3e000000, v18
	ds_read2_b32 v[22:23], v115 offset0:186 offset1:217
	v_cndmask_b32_e64 v17, v84, v12, s[0:1]
	ds_read2_b32 v[24:25], v116 offset0:186 offset1:217
	v_max3_f32 v12, v26, v16, v17
	ds_read2_b32 v[26:27], v118 offset0:186 offset1:217
	ds_read2_b32 v[28:29], v119 offset0:186 offset1:217
	ds_read2_b32 v[30:31], v121 offset0:186 offset1:217
	ds_read2_b32 v[32:33], v122 offset0:186 offset1:217
	s_waitcnt lgkmcnt(5)
	v_fmamk_f32 v13, v14, 0x3e000000, v22
	v_cndmask_b32_e64 v18, v84, v13, s[4:5]
	s_waitcnt lgkmcnt(4)
	v_fmamk_f32 v13, v15, 0x3e000000, v24
	s_waitcnt lgkmcnt(3)
	v_fmamk_f32 v8, v8, 0x3e000000, v26
	v_cndmask_b32_e64 v15, v84, v13, s[8:9]
	v_cndmask_b32_e64 v14, v84, v8, s[10:11]
	s_waitcnt lgkmcnt(2)
	v_fmamk_f32 v8, v9, 0x3e000000, v28
	v_max3_f32 v12, v12, v18, v15
	v_cndmask_b32_e64 v13, v84, v8, s[12:13]
	s_waitcnt lgkmcnt(1)
	v_fmamk_f32 v9, v10, 0x3e000000, v30
	v_max3_f32 v8, v12, v14, v13
	v_cndmask_b32_e64 v12, v84, v9, s[14:15]
	s_waitcnt lgkmcnt(0)
	v_fmamk_f32 v9, v11, 0x3e000000, v32
	v_cndmask_b32_e64 v11, v84, v9, s[16:17]
	v_fmac_f32_e32 v21, 0x3e000000, v4
	v_fmac_f32_e32 v19, 0x3e000000, v5
	v_max3_f32 v8, v8, v12, v11
	v_cndmask_b32_e32 v10, v84, v21, vcc
	v_cndmask_b32_e64 v9, v84, v19, s[0:1]
	v_fmac_f32_e32 v23, 0x3e000000, v6
	v_fmac_f32_e32 v25, 0x3e000000, v7
	v_max3_f32 v4, v8, v10, v9
	v_cndmask_b32_e64 v8, v84, v23, s[4:5]
	v_cndmask_b32_e64 v6, v84, v25, s[8:9]
	v_fmac_f32_e32 v27, 0x3e000000, v0
	v_fmac_f32_e32 v29, 0x3e000000, v1
	v_max3_f32 v7, v4, v8, v6
	v_cndmask_b32_e64 v5, v84, v27, s[10:11]
	v_cndmask_b32_e64 v4, v84, v29, s[12:13]
	v_fmac_f32_e32 v31, 0x3e000000, v2
	v_fmac_f32_e32 v33, 0x3e000000, v3
	v_max3_f32 v7, v7, v5, v4
	v_cndmask_b32_e64 v1, v84, v31, s[14:15]
	v_cndmask_b32_e64 v0, v84, v33, s[16:17]
	v_max3_f32 v2, v7, v1, v0
	ds_bpermute_b32 v3, v73, v2
	s_lshr_b32 s0, s46, 3
	s_cmpk_eq_i32 s87, 0x7440
	s_waitcnt lgkmcnt(0)
	v_max_f32_e32 v3, v3, v3
	v_max_f32_e32 v2, v2, v3
	ds_bpermute_b32 v3, v74, v2
	s_waitcnt lgkmcnt(0)
	v_max_f32_e32 v3, v3, v3
	v_max_f32_e32 v2, v2, v3
	v_sub_f32_e32 v20, v117, v2
	v_mul_f32_e32 v20, 0x3fb8aa3b, v20
	v_exp_f32_e32 v115, v20
	v_sub_f32_e32 v20, v106, v2
	v_mul_f32_e32 v20, 0x3fb8aa3b, v20
	v_exp_f32_e32 v118, v20
	v_sub_f32_e32 v20, v120, v2
	v_mul_f32_e32 v20, 0x3fb8aa3b, v20
	v_exp_f32_e32 v128, v20
	v_sub_f32_e32 v20, v108, v2
	v_mul_f32_e32 v20, 0x3fb8aa3b, v20
	v_exp_f32_e32 v129, v20
	v_sub_f32_e32 v20, v96, v2
	v_mul_f32_e32 v20, 0x3fb8aa3b, v20
	v_exp_f32_e32 v130, v20
	v_sub_f32_e32 v20, v97, v2
	v_mul_f32_e32 v20, 0x3fb8aa3b, v20
	v_exp_f32_e32 v131, v20
	v_sub_f32_e32 v20, v102, v2
	v_mul_f32_e32 v20, 0x3fb8aa3b, v20
	v_exp_f32_e32 v142, v20
	v_sub_f32_e32 v20, v103, v2
	v_mul_f32_e32 v20, 0x3fb8aa3b, v20
	v_exp_f32_e32 v143, v20
	v_sub_f32_e32 v20, v104, v2
	v_mul_f32_e32 v20, 0x3fb8aa3b, v20
	v_exp_f32_e32 v144, v20
	v_sub_f32_e32 v20, v105, v2
	v_mul_f32_e32 v20, 0x3fb8aa3b, v20
	v_exp_f32_e32 v145, v20
	v_sub_f32_e32 v20, v98, v2
	v_mul_f32_e32 v20, 0x3fb8aa3b, v20
	v_exp_f32_e32 v146, v20
	v_sub_f32_e32 v20, v99, v2
	v_mul_f32_e32 v20, 0x3fb8aa3b, v20
	v_exp_f32_e32 v147, v20
	v_sub_f32_e32 v20, v100, v2
	v_mul_f32_e32 v20, 0x3fb8aa3b, v20
	v_exp_f32_e32 v148, v20
	v_sub_f32_e32 v20, v101, v2
	v_mul_f32_e32 v20, 0x3fb8aa3b, v20
	v_exp_f32_e32 v149, v20
	v_sub_f32_e32 v20, v86, v2
	v_mul_f32_e32 v20, 0x3fb8aa3b, v20
	v_exp_f32_e32 v152, v20
	v_sub_f32_e32 v20, v88, v2
	v_mul_f32_e32 v20, 0x3fb8aa3b, v20
	v_exp_f32_e32 v153, v20
	v_sub_f32_e32 v20, v90, v2
	v_mul_f32_e32 v20, 0x3fb8aa3b, v20
	v_exp_f32_e32 v154, v20
	v_sub_f32_e32 v20, v44, v2
	v_mul_f32_e32 v20, 0x3fb8aa3b, v20
	v_exp_f32_e32 v155, v20
	v_sub_f32_e32 v20, v92, v2
	v_mul_f32_e32 v20, 0x3fb8aa3b, v20
	v_exp_f32_e32 v156, v20
	v_sub_f32_e32 v20, v46, v2
	v_mul_f32_e32 v20, 0x3fb8aa3b, v20
	v_exp_f32_e32 v157, v20
	v_sub_f32_e32 v20, v42, v2
	v_mul_f32_e32 v20, 0x3fb8aa3b, v20
	v_exp_f32_e32 v158, v20
	v_sub_f32_e32 v20, v43, v2
	v_mul_f32_e32 v20, 0x3fb8aa3b, v20
	v_exp_f32_e32 v159, v20
	v_sub_f32_e32 v20, v87, v2
	v_mul_f32_e32 v20, 0x3fb8aa3b, v20
	v_exp_f32_e32 v160, v20
	v_sub_f32_e32 v20, v89, v2
	v_mul_f32_e32 v20, 0x3fb8aa3b, v20
	v_exp_f32_e32 v161, v20
	v_sub_f32_e32 v20, v91, v2
	v_mul_f32_e32 v20, 0x3fb8aa3b, v20
	v_exp_f32_e32 v162, v20
	v_sub_f32_e32 v20, v45, v2
	v_mul_f32_e32 v20, 0x3fb8aa3b, v20
	v_exp_f32_e32 v163, v20
	v_sub_f32_e32 v20, v93, v2
	v_mul_f32_e32 v20, 0x3fb8aa3b, v20
	v_exp_f32_e32 v164, v20
	v_sub_f32_e32 v20, v47, v2
	v_mul_f32_e32 v20, 0x3fb8aa3b, v20
	v_exp_f32_e32 v165, v20
	v_sub_f32_e32 v20, v94, v2
	v_mul_f32_e32 v20, 0x3fb8aa3b, v20
	v_exp_f32_e32 v166, v20
	v_sub_f32_e32 v20, v95, v2
	v_mul_f32_e32 v20, 0x3fb8aa3b, v20
	v_exp_f32_e32 v167, v20
	v_sub_f32_e32 v20, v107, v2
	v_mul_f32_e32 v20, 0x3fb8aa3b, v20
	v_exp_f32_e32 v168, v20
	v_sub_f32_e32 v20, v34, v2
	v_mul_f32_e32 v20, 0x3fb8aa3b, v20
	v_exp_f32_e32 v169, v20
	v_sub_f32_e32 v20, v36, v2
	v_sub_f32_e32 v3, v50, v2
	v_mul_f32_e32 v20, 0x3fb8aa3b, v20
	v_mul_f32_e32 v3, 0x3fb8aa3b, v3
	v_sub_f32_e32 v7, v114, v2
	v_exp_f32_e32 v170, v20
	v_sub_f32_e32 v20, v109, v2
	v_exp_f32_e32 v3, v3
	v_mul_f32_e32 v7, 0x3fb8aa3b, v7
	v_mul_f32_e32 v20, 0x3fb8aa3b, v20
	v_exp_f32_e32 v7, v7
	v_exp_f32_e32 v171, v20
	v_sub_f32_e32 v20, v38, v2
	v_mul_f32_e32 v20, 0x3fb8aa3b, v20
	v_exp_f32_e32 v172, v20
	v_sub_f32_e32 v20, v110, v2
	v_add_f32_e32 v19, 0, v3
	v_mul_f32_e32 v20, 0x3fb8aa3b, v20
	v_add_f32_e32 v19, v7, v19
	v_exp_f32_e32 v173, v20
	v_sub_f32_e32 v20, v40, v2
	v_add_f32_e32 v19, v115, v19
	v_mul_f32_e32 v20, 0x3fb8aa3b, v20
; __device__ __forceinline__ unsigned pk2(float lo, float hi) { unsigned r; asm("v_cvt_pk_bf16_f32 %0, %1, %2" : "=v"(r) : "v"(lo), "v"(hi)); return r; }
; __device__ __forceinline__ void na_phase(const Frame& F, const bf16* QH, const bf16* VB, const float* rpb, bf16* U) {
;     ...
;                 for (int e = 0; e < 4; ++e) { const float p = __builtin_amdgcn_exp2f((acc[blk][e] - mx) * 1.44269504089f); acc[blk][e] = p; sum += p; }
;             sum += __shfl_xor(sum, 16); sum += __shfl_xor(sum, 32);
;             const float inv = 1.0f / sum;
;             f32x4 o[4];
; #pragma unroll
;             for (int db = 0; db < 4; ++db) o[db] = (f32x4){0.f, 0.f, 0.f, 0.f};
; #pragma unroll
;             for (int i = 0; i < 8; ++i) {
;                 v4u pw; pw.x = pk2(acc[2 * i][0], acc[2 * i][1]); pw.y = pk2(acc[2 * i][2], acc[2 * i][3]); pw.z = pk2(acc[2 * i + 1][0], acc[2 * i + 1][1]); pw.w = pk2(acc[2 * i + 1][2], acc[2 * i + 1][3]);
;                 const bf16x8 pf = __builtin_bit_cast(bf16x8, pw);
;                 const size_t vrow = (((size_t)h * 512 + b * 256 + rs + i) * 8 + (c0 >> 3) + q4) * 512;
; #pragma unroll
;                 for (int db = 0; db < 4; ++db) { const bf16x8 vfrag = *(const bf16x8*)(VB + vrow + (16 * db + n) * 8);
;                     o[db] = __builtin_amdgcn_mfma_f32_16x16x32_bf16(vfrag, pf, o[db], 0, 0, 0); }
;             }
	v_add_f32_e32 v19, v118, v19
	v_exp_f32_e32 v174, v20
	v_sub_f32_e32 v20, v111, v2
	v_add_f32_e32 v19, v128, v19
	v_mul_f32_e32 v20, 0x3fb8aa3b, v20
	v_add_f32_e32 v19, v129, v19
	v_exp_f32_e32 v175, v20
	v_sub_f32_e32 v20, v123, v2
	v_add_lshl_u32 v50, s0, v72, 10
	v_add_f32_e32 v19, v130, v19
	v_mul_f32_e32 v24, 0x3fb8aa3b, v20
	v_lshl_add_u64 v[20:21], v[60:61], 0, v[50:51]
	v_sub_f32_e32 v28, v35, v2
	v_add_f32_e32 v19, v131, v19
	v_lshl_add_u64 v[150:151], s[70:71], 0, v[20:21]
	v_mul_f32_e32 v34, 0x3fb8aa3b, v28
	v_add_f32_e32 v19, v142, v19
	v_add_co_u32_e32 v32, vcc, s78, v150
	v_exp_f32_e32 v176, v34
	v_sub_f32_e32 v34, v37, v2
	v_add_f32_e32 v19, v143, v19
	v_addc_co_u32_e32 v33, vcc, 0, v151, vcc
	v_mul_f32_e32 v34, 0x3fb8aa3b, v34
	v_add_f32_e32 v19, v144, v19
	global_load_dwordx4 v[20:23], v[32:33], off
	v_exp_f32_e32 v50, v24
	global_load_dwordx4 v[24:27], v[32:33], off offset:256
	v_exp_f32_e32 v177, v34
	v_sub_f32_e32 v34, v124, v2
	v_add_co_u32_e32 v86, vcc, s79, v150
	v_add_f32_e32 v19, v145, v19
	v_mul_f32_e32 v36, 0x3fb8aa3b, v34
	v_addc_co_u32_e32 v87, vcc, 0, v151, vcc
	v_add_f32_e32 v19, v146, v19
	global_load_dwordx4 v[28:31], v[32:33], off offset:512
	v_exp_f32_e32 v178, v36
	global_load_dwordx4 v[36:39], v[86:87], off
	v_sub_f32_e32 v44, v125, v2
	global_load_dwordx4 v[32:35], v[32:33], off offset:768
	v_add_f32_e32 v19, v147, v19
	v_mul_f32_e32 v44, 0x3fb8aa3b, v44
	v_add_f32_e32 v19, v148, v19
	global_load_dwordx4 v[40:43], v[86:87], off offset:256
	v_exp_f32_e32 v179, v44
	v_sub_f32_e32 v44, v126, v2
	v_sub_f32_e32 v88, v127, v2
	v_add_co_u32_e32 v102, vcc, s80, v150
	v_add_f32_e32 v19, v149, v19
	v_mul_f32_e32 v44, 0x3fb8aa3b, v44
	v_mul_f32_e32 v88, 0x3fb8aa3b, v88
	v_addc_co_u32_e32 v103, vcc, 0, v151, vcc
	v_add_f32_e32 v19, v152, v19
	v_exp_f32_e32 v180, v44
	global_load_dwordx4 v[44:47], v[86:87], off offset:512
	global_load_dwordx4 v[90:93], v[102:103], off
	v_exp_f32_e32 v181, v88
	global_load_dwordx4 v[86:89], v[86:87], off offset:768
	v_add_f32_e32 v19, v153, v19
	v_add_f32_e32 v19, v154, v19
	v_add_f32_e32 v19, v155, v19
	v_add_f32_e32 v19, v156, v19
	v_add_f32_e32 v19, v157, v19
	v_add_f32_e32 v19, v158, v19
	v_add_f32_e32 v19, v159, v19
	v_add_f32_e32 v19, v160, v19
	v_add_f32_e32 v19, v161, v19
	v_add_f32_e32 v19, v162, v19
	v_add_f32_e32 v19, v163, v19
	v_add_f32_e32 v19, v164, v19
	v_add_f32_e32 v19, v165, v19
	v_add_f32_e32 v19, v166, v19
	v_add_f32_e32 v19, v167, v19
	v_add_f32_e32 v19, v168, v19
	v_add_f32_e32 v19, v169, v19
	v_add_f32_e32 v19, v170, v19
	v_add_f32_e32 v19, v171, v19
	v_add_f32_e32 v19, v172, v19
	v_add_f32_e32 v19, v173, v19
	global_load_dwordx4 v[98:101], v[102:103], off offset:512
	v_add_f32_e32 v19, v174, v19
	v_add_f32_e32 v19, v175, v19
	v_add_f32_e32 v19, v50, v19
	v_add_f32_e32 v19, v176, v19
	v_sub_f32_e32 v94, v112, v2
	v_add_f32_e32 v19, v177, v19
	v_mul_f32_e32 v94, 0x3fb8aa3b, v94
	v_sub_f32_e32 v16, v16, v2
	v_add_f32_e32 v19, v178, v19
	v_exp_f32_e32 v182, v94
	v_mul_f32_e32 v16, 0x3fb8aa3b, v16
	v_add_f32_e32 v19, v179, v19
	global_load_dwordx4 v[94:97], v[102:103], off offset:256
	v_exp_f32_e32 v183, v16
	v_add_f32_e32 v19, v180, v19
	v_add_f32_e32 v19, v181, v19
	v_sub_f32_e32 v16, v17, v2
	v_sub_f32_e32 v107, v18, v2
	v_add_co_u32_e32 v116, vcc, s81, v150
	v_add_f32_e32 v106, v182, v19
	v_mul_f32_e32 v16, 0x3fb8aa3b, v16
	v_addc_co_u32_e32 v117, vcc, 0, v151, vcc
	v_mul_f32_e32 v107, 0x3fb8aa3b, v107
	v_exp_f32_e32 v184, v16
	global_load_dwordx4 v[16:19], v[116:117], off
	v_exp_f32_e32 v185, v107
	global_load_dwordx4 v[102:105], v[102:103], off offset:768
	v_add_f32_e32 v110, v183, v106
	global_load_dwordx4 v[106:109], v[116:117], off offset:256
	v_add_f32_e32 v110, v184, v110
	v_add_f32_e32 v132, v185, v110
	global_load_dwordx4 v[110:113], v[116:117], off offset:512
	v_cvt_pk_bf16_f32 v114, v3, v7
	v_cvt_pk_bf16_f32 v115, v115, v118
	global_load_dwordx4 v[118:121], v[116:117], off offset:768
	v_add_co_u32_e32 v134, vcc, s82, v150
	v_cvt_pk_bf16_f32 v116, v128, v129
	v_cvt_pk_bf16_f32 v117, v130, v131
	v_sub_f32_e32 v15, v15, v2
	s_waitcnt vmcnt(15)
	v_mfma_f32_16x16x32_bf16 v[20:23], v[20:23], v[114:117], 0
	v_addc_co_u32_e32 v135, vcc, 0, v151, vcc
	v_mul_f32_e32 v15, 0x3fb8aa3b, v15
	s_waitcnt vmcnt(14)
	v_mfma_f32_16x16x32_bf16 v[24:27], v[24:27], v[114:117], 0
	v_sub_f32_e32 v7, v14, v2
	v_add_co_u32_e32 v14, vcc, s83, v150
	s_waitcnt vmcnt(11)
	v_mfma_f32_16x16x32_bf16 v[32:35], v[32:35], v[114:117], 0
	v_exp_f32_e32 v186, v15
	v_addc_co_u32_e32 v15, vcc, 0, v151, vcc
	v_mfma_f32_16x16x32_bf16 v[28:31], v[28:31], v[114:117], 0
	global_load_dwordx4 v[138:141], v[14:15], off
	v_cvt_pk_bf16_f32 v114, v142, v143
	v_cvt_pk_bf16_f32 v115, v144, v145
	global_load_dwordx4 v[142:145], v[14:15], off offset:256
	v_cvt_pk_bf16_f32 v116, v146, v147
	v_cvt_pk_bf16_f32 v117, v148, v149
	global_load_dwordx4 v[122:125], v[134:135], off
	global_load_dwordx4 v[126:129], v[134:135], off offset:256
	v_mfma_f32_16x16x32_bf16 v[20:23], v[36:39], v[114:117], v[20:23]
	global_load_dwordx4 v[36:39], v[14:15], off offset:512
	v_add_f32_e32 v3, v186, v132
	global_load_dwordx4 v[130:133], v[134:135], off offset:512
	s_waitcnt vmcnt(16)
	v_mfma_f32_16x16x32_bf16 v[24:27], v[40:43], v[114:117], v[24:27]
	global_load_dwordx4 v[40:43], v[14:15], off offset:768
	v_add_co_u32_e32 v14, vcc, s84, v150
	s_waitcnt vmcnt(14)
; __device__ __forceinline__ unsigned pk2(float lo, float hi) { unsigned r; asm("v_cvt_pk_bf16_f32 %0, %1, %2" : "=v"(r) : "v"(lo), "v"(hi)); return r; }
; __device__ __forceinline__ void na_phase(const Frame& F, const bf16* QH, const bf16* VB, const float* rpb, bf16* U) {
;     ...
;             sum += __shfl_xor(sum, 16); sum += __shfl_xor(sum, 32);
;             const float inv = 1.0f / sum;
;             f32x4 o[4];
; #pragma unroll
;             for (int db = 0; db < 4; ++db) o[db] = (f32x4){0.f, 0.f, 0.f, 0.f};
; #pragma unroll
;             for (int i = 0; i < 8; ++i) {
;                 v4u pw; pw.x = pk2(acc[2 * i][0], acc[2 * i][1]); pw.y = pk2(acc[2 * i][2], acc[2 * i][3]); pw.z = pk2(acc[2 * i + 1][0], acc[2 * i + 1][1]); pw.w = pk2(acc[2 * i + 1][2], acc[2 * i + 1][3]);
;                 const bf16x8 pf = __builtin_bit_cast(bf16x8, pw);
;                 const size_t vrow = (((size_t)h * 512 + b * 256 + rs + i) * 8 + (c0 >> 3) + q4) * 512;
; #pragma unroll
;                 for (int db = 0; db < 4; ++db) { const bf16x8 vfrag = *(const bf16x8*)(VB + vrow + (16 * db + n) * 8);
;                     o[db] = __builtin_amdgcn_mfma_f32_16x16x32_bf16(vfrag, pf, o[db], 0, 0, 0); }
;             }
; #pragma unroll
;             for (int db = 0; db < 4; ++db) { v2u w; w.x = pk2(o[db][0] * inv, o[db][1] * inv); w.y = pk2(o[db][2] * inv, o[db][3] * inv);
;                 *(v2u*)(U + tokq * DM + h * 64 + 16 * db + 4 * q4) = w; }
	v_mfma_f32_16x16x32_bf16 v[32:35], v[86:89], v[114:117], v[32:35]
	v_addc_co_u32_e32 v15, vcc, 0, v151, vcc
	v_cvt_pk_bf16_f32 v87, v154, v155
	v_add_co_u32_e32 v154, vcc, s85, v150
	v_cvt_pk_bf16_f32 v86, v152, v153
	global_load_dwordx4 v[146:149], v[14:15], off
	s_nop 0
	v_addc_co_u32_e32 v155, vcc, 0, v151, vcc
	global_load_dwordx4 v[150:153], v[154:155], off
	v_mfma_f32_16x16x32_bf16 v[28:31], v[44:47], v[114:117], v[28:31]
	global_load_dwordx4 v[134:137], v[134:135], off offset:768
	v_cvt_pk_bf16_f32 v88, v156, v157
	global_load_dwordx4 v[44:47], v[14:15], off offset:256
	global_load_dwordx4 v[114:117], v[14:15], off offset:512
	v_cvt_pk_bf16_f32 v89, v158, v159
	v_mul_f32_e32 v7, 0x3fb8aa3b, v7
	v_mfma_f32_16x16x32_bf16 v[20:23], v[90:93], v[86:89], v[20:23]
	global_load_dwordx4 v[90:93], v[14:15], off offset:768
	v_exp_f32_e32 v187, v7
	v_sub_f32_e32 v7, v13, v2
	v_mul_f32_e32 v7, 0x3fb8aa3b, v7
	v_exp_f32_e32 v188, v7
	v_sub_f32_e32 v7, v12, v2
	s_waitcnt vmcnt(19)
	v_mfma_f32_16x16x32_bf16 v[12:15], v[98:101], v[86:89], v[28:31]
	v_mul_f32_e32 v7, 0x3fb8aa3b, v7
	v_exp_f32_e32 v156, v7
	v_sub_f32_e32 v7, v11, v2
	global_load_dwordx4 v[28:31], v[154:155], off offset:256
	s_waitcnt vmcnt(19)
	v_mfma_f32_16x16x32_bf16 v[24:27], v[94:97], v[86:89], v[24:27]
	global_load_dwordx4 v[94:97], v[154:155], off offset:512
	v_mul_f32_e32 v7, 0x3fb8aa3b, v7
	v_exp_f32_e32 v98, v7
	s_waitcnt vmcnt(18)
	v_mfma_f32_16x16x32_bf16 v[32:35], v[102:105], v[86:89], v[32:35]
	v_cvt_pk_bf16_f32 v86, v160, v161
	v_cvt_pk_bf16_f32 v87, v162, v163
	v_cvt_pk_bf16_f32 v88, v164, v165
	v_cvt_pk_bf16_f32 v89, v166, v167
	v_sub_f32_e32 v7, v10, v2
	v_mfma_f32_16x16x32_bf16 v[16:19], v[16:19], v[86:89], v[20:23]
	v_mul_f32_e32 v7, 0x3fb8aa3b, v7
	v_exp_f32_e32 v99, v7
	v_sub_f32_e32 v7, v9, v2
	s_waitcnt vmcnt(17)
	v_mfma_f32_16x16x32_bf16 v[20:23], v[106:109], v[86:89], v[24:27]
	v_mul_f32_e32 v7, 0x3fb8aa3b, v7
	v_add_f32_e32 v3, v187, v3
	v_exp_f32_e32 v100, v7
	global_load_dwordx4 v[24:27], v[154:155], off offset:768
	s_waitcnt vmcnt(17)
	v_mfma_f32_16x16x32_bf16 v[10:13], v[110:113], v[86:89], v[12:15]
	v_sub_f32_e32 v7, v8, v2
	v_add_f32_e32 v3, v188, v3
	v_mul_f32_e32 v7, 0x3fb8aa3b, v7
	s_waitcnt vmcnt(16)
	v_mfma_f32_16x16x32_bf16 v[32:35], v[118:121], v[86:89], v[32:35]
	v_sub_f32_e32 v6, v6, v2
	v_add_f32_e32 v3, v156, v3
	v_exp_f32_e32 v101, v7
	v_mul_f32_e32 v6, 0x3fb8aa3b, v6
	v_sub_f32_e32 v5, v5, v2
	v_cvt_pk_bf16_f32 v86, v168, v169
	v_add_f32_e32 v3, v98, v3
	v_exp_f32_e32 v102, v6
	v_mul_f32_e32 v5, 0x3fb8aa3b, v5
	v_cvt_pk_bf16_f32 v87, v170, v171
	v_cvt_pk_bf16_f32 v88, v172, v173
	v_cvt_pk_bf16_f32 v89, v174, v175
	v_add_f32_e32 v3, v99, v3
	s_waitcnt vmcnt(13)
	v_mfma_f32_16x16x32_bf16 v[14:17], v[122:125], v[86:89], v[16:19]
	v_add_f32_e32 v3, v100, v3
	v_add_f32_e32 v3, v101, v3
	v_add_f32_e32 v3, v102, v3
	s_waitcnt vmcnt(12)
	v_mfma_f32_16x16x32_bf16 v[18:21], v[126:129], v[86:89], v[20:23]
	v_sub_f32_e32 v1, v1, v2
	v_mul_f32_e32 v1, 0x3fb8aa3b, v1
	v_sub_f32_e32 v0, v0, v2
	s_waitcnt vmcnt(10)
	v_mfma_f32_16x16x32_bf16 v[8:11], v[130:133], v[86:89], v[10:13]
	v_mul_f32_e32 v0, 0x3fb8aa3b, v0
	v_lshl_add_u64 v[60:61], v[60:61], 0, s[48:49]
	s_waitcnt vmcnt(6)
	v_mfma_f32_16x16x32_bf16 v[32:35], v[134:137], v[86:89], v[32:35]
	v_cvt_pk_bf16_f32 v86, v50, v176
	v_exp_f32_e32 v50, v5
	v_cvt_pk_bf16_f32 v87, v177, v178
	v_cvt_pk_bf16_f32 v88, v179, v180
	v_cvt_pk_bf16_f32 v89, v181, v182
	s_nop 0
	v_add_f32_e32 v5, v50, v3
	v_sub_f32_e32 v3, v4, v2
	v_mfma_f32_16x16x32_bf16 v[12:15], v[138:141], v[86:89], v[14:17]
	v_mul_f32_e32 v3, 0x3fb8aa3b, v3
	v_mfma_f32_16x16x32_bf16 v[6:9], v[36:39], v[86:89], v[8:11]
	v_exp_f32_e32 v36, v3
	v_exp_f32_e32 v37, v1
	v_exp_f32_e32 v38, v0
	v_mfma_f32_16x16x32_bf16 v[16:19], v[142:145], v[86:89], v[18:21]
	v_add_f32_e32 v4, v36, v5
	v_add_f32_e32 v4, v37, v4
	v_add_f32_e32 v39, v38, v4
	v_mfma_f32_16x16x32_bf16 v[20:23], v[40:43], v[86:89], v[32:35]
	v_cvt_pk_bf16_f32 v32, v183, v184
	v_cvt_pk_bf16_f32 v33, v185, v186
	v_cvt_pk_bf16_f32 v34, v187, v188
	v_cvt_pk_bf16_f32 v35, v156, v98
	s_nop 0
	v_mfma_f32_16x16x32_bf16 v[10:13], v[146:149], v[32:35], v[12:15]
	s_waitcnt vmcnt(5)
	v_mfma_f32_16x16x32_bf16 v[14:17], v[44:47], v[32:35], v[16:19]
	v_cvt_pk_bf16_f32 v18, v99, v100
	v_cvt_pk_bf16_f32 v19, v101, v102
	s_waitcnt vmcnt(4)
	v_mfma_f32_16x16x32_bf16 v[0:3], v[114:117], v[32:35], v[6:9]
	s_waitcnt vmcnt(3)
	v_mfma_f32_16x16x32_bf16 v[4:7], v[90:93], v[32:35], v[20:23]
	v_cvt_pk_bf16_f32 v20, v50, v36
	v_cvt_pk_bf16_f32 v21, v37, v38
	s_nop 0
	v_mfma_f32_16x16x32_bf16 v[8:11], v[150:153], v[18:21], v[10:13]
	s_nop 2
	ds_bpermute_b32 v12, v73, v39
	s_waitcnt vmcnt(1)
	v_mfma_f32_16x16x32_bf16 v[0:3], v[94:97], v[18:21], v[0:3]
	s_waitcnt lgkmcnt(0)
	v_add_f32_e32 v22, v39, v12
	v_mfma_f32_16x16x32_bf16 v[12:15], v[28:31], v[18:21], v[14:17]
	s_nop 2
	ds_bpermute_b32 v16, v74, v22
	s_waitcnt vmcnt(0)
	v_mfma_f32_16x16x32_bf16 v[4:7], v[24:27], v[18:21], v[4:7]
	s_waitcnt lgkmcnt(0)
	v_add_f32_e32 v16, v22, v16
	v_div_scale_f32 v17, s[0:1], v16, v16, 1.0
	v_rcp_f32_e32 v22, v17
	s_nop 0
	v_fma_f32 v18, -v17, v22, 1.0
	v_fmac_f32_e32 v22, v18, v22
	v_div_scale_f32 v18, vcc, 1.0, v16, 1.0
	v_mul_f32_e32 v19, v18, v22
	v_fma_f32 v20, -v17, v19, v18
	v_fmac_f32_e32 v19, v20, v22
	v_fma_f32 v17, -v17, v19, v18
	v_div_fmas_f32 v17, v17, v22, v19
	v_div_fixup_f32 v18, v17, v16, 1.0
	v_mul_f32_e32 v8, v18, v8
	v_mul_f32_e32 v9, v18, v9
	v_mul_f32_e32 v0, v18, v0
	v_mul_f32_e32 v1, v18, v1
	v_cvt_pk_bf16_f32 v8, v8, v9
	v_mul_f32_e32 v9, v18, v10
	v_cvt_pk_bf16_f32 v0, v0, v1
	v_mul_f32_e32 v1, v18, v2
	v_lshl_add_u64 v[16:17], s[70:71], 0, v[62:63]
	v_mul_f32_e32 v10, v18, v11
	v_cvt_pk_bf16_f32 v9, v9, v10
	v_mul_f32_e32 v2, v18, v3
	v_cvt_pk_bf16_f32 v1, v1, v2
	global_store_dwordx2 v[16:17], v[8:9], off offset:-64
	v_mul_f32_e32 v8, v18, v12
	v_mul_f32_e32 v9, v18, v13
	global_store_dwordx2 v[16:17], v[0:1], off
	v_mul_f32_e32 v0, v18, v4
	v_mul_f32_e32 v1, v18, v5
	v_cvt_pk_bf16_f32 v8, v8, v9
	v_mul_f32_e32 v9, v18, v14
	v_cvt_pk_bf16_f32 v0, v0, v1
	v_mul_f32_e32 v1, v18, v6
	v_lshl_add_u64 v[62:63], v[62:63], 0, s[50:51]
	v_mul_f32_e32 v10, v18, v15
	v_cvt_pk_bf16_f32 v9, v9, v10
	global_store_dwordx2 v[16:17], v[8:9], off offset:-32
	v_mul_f32_e32 v2, v18, v7
	v_cvt_pk_bf16_f32 v1, v1, v2
	global_store_dwordx2 v[16:17], v[0:1], off offset:32
	s_cbranch_scc1 .LBB0_904
